# v93 + redundant s_setprio 0/1 pairs removed from inside the 32-MFMA runs of the GEMM K loops
# baseline (speedup 1.0000x reference)
.LBB0_306:
	ds_read_b128 v[148:151], v163
	ds_read_b128 v[168:171], v163 offset:1024
	ds_read_b128 v[172:175], v163 offset:2048
	ds_read_b128 v[176:179], v163 offset:3072
	ds_read_b128 v[180:183], v164
	ds_read_b128 v[184:187], v164 offset:1024
	ds_read_b128 v[188:191], v164 offset:2048
	ds_read_b128 v[192:195], v164 offset:3072
	s_add_u32 s28, s26, 0xfffc0080
	s_addc_u32 s29, s27, -1
	s_cmp_eq_u32 s58, 12
	s_cselect_b32 s31, s5, s29
	s_cselect_b32 s30, s7, s28
	s_cselect_b32 s29, s19, s57
	s_cselect_b32 s28, s21, s56
	v_lshl_add_u64 v[152:153], s[26:27], 0, v[140:141]
	s_add_i32 m0, s39, 0xc000
	ds_read_b128 v[196:199], v165
	ds_read_b128 v[200:203], v165 offset:1024
	ds_read_b128 v[204:207], v165 offset:2048
	ds_read_b128 v[208:211], v165 offset:3072
	ds_read_b128 v[212:215], v165 offset:4096
	ds_read_b128 v[216:219], v165 offset:5120
	ds_read_b128 v[220:223], v165 offset:6144
	ds_read_b128 v[224:227], v165 offset:7168
	global_load_lds_dwordx4 v[152:153], off
	v_lshl_add_u64 v[152:153], s[26:27], 0, v[142:143]
	s_add_i32 m0, s39, 0xe000
	s_nop 0
	global_load_lds_dwordx4 v[152:153], off
	s_waitcnt vmcnt(8)
	s_waitcnt lgkmcnt(0)
	s_barrier
	s_setprio 1
	s_waitcnt lgkmcnt(0)
	v_mfma_f32_16x16x32_bf16 v[124:127], v[148:151], v[196:199], v[124:127]
	v_mfma_f32_16x16x32_bf16 v[120:123], v[172:175], v[196:199], v[120:123]
	v_mfma_f32_16x16x32_bf16 v[108:111], v[148:151], v[204:207], v[108:111]
	v_mfma_f32_16x16x32_bf16 v[104:107], v[172:175], v[204:207], v[104:107]
	v_mfma_f32_16x16x32_bf16 v[92:95], v[148:151], v[212:215], v[92:95]
	v_mfma_f32_16x16x32_bf16 v[88:91], v[172:175], v[212:215], v[88:91]
	v_mfma_f32_16x16x32_bf16 v[76:79], v[148:151], v[220:223], v[76:79]
	v_mfma_f32_16x16x32_bf16 v[72:75], v[172:175], v[220:223], v[72:75]
	v_mfma_f32_16x16x32_bf16 v[124:127], v[168:171], v[200:203], v[124:127]
	v_mfma_f32_16x16x32_bf16 v[120:123], v[176:179], v[200:203], v[120:123]
	v_mfma_f32_16x16x32_bf16 v[108:111], v[168:171], v[208:211], v[108:111]
	v_mfma_f32_16x16x32_bf16 v[104:107], v[176:179], v[208:211], v[104:107]
	v_mfma_f32_16x16x32_bf16 v[92:95], v[168:171], v[216:219], v[92:95]
	v_mfma_f32_16x16x32_bf16 v[88:91], v[176:179], v[216:219], v[88:91]
	v_mfma_f32_16x16x32_bf16 v[76:79], v[168:171], v[224:227], v[76:79]
	v_mfma_f32_16x16x32_bf16 v[72:75], v[176:179], v[224:227], v[72:75]
	v_mfma_f32_16x16x32_bf16 v[116:119], v[180:183], v[196:199], v[116:119]
	v_mfma_f32_16x16x32_bf16 v[112:115], v[188:191], v[196:199], v[112:115]
	v_mfma_f32_16x16x32_bf16 v[100:103], v[180:183], v[204:207], v[100:103]
	v_mfma_f32_16x16x32_bf16 v[96:99], v[188:191], v[204:207], v[96:99]
	v_mfma_f32_16x16x32_bf16 v[84:87], v[180:183], v[212:215], v[84:87]
	v_mfma_f32_16x16x32_bf16 v[80:83], v[188:191], v[212:215], v[80:83]
	v_mfma_f32_16x16x32_bf16 v[68:71], v[180:183], v[220:223], v[68:71]
	v_mfma_f32_16x16x32_bf16 v[64:67], v[188:191], v[220:223], v[64:67]
	v_mfma_f32_16x16x32_bf16 v[116:119], v[184:187], v[200:203], v[116:119]
	v_mfma_f32_16x16x32_bf16 v[112:115], v[192:195], v[200:203], v[112:115]
	v_mfma_f32_16x16x32_bf16 v[100:103], v[184:187], v[208:211], v[100:103]
	v_mfma_f32_16x16x32_bf16 v[96:99], v[192:195], v[208:211], v[96:99]
	v_mfma_f32_16x16x32_bf16 v[84:87], v[184:187], v[216:219], v[84:87]
	v_mfma_f32_16x16x32_bf16 v[80:83], v[192:195], v[216:219], v[80:83]
	v_mfma_f32_16x16x32_bf16 v[68:71], v[184:187], v[224:227], v[68:71]
	v_mfma_f32_16x16x32_bf16 v[64:67], v[192:195], v[224:227], v[64:67]
	s_setprio 0
	s_barrier
	s_add_i32 s59, s50, s38
	v_lshl_add_u64 v[152:153], s[28:29], 0, v[128:129]
	s_mov_b32 m0, s59
	ds_read_b128 v[196:199], v165 offset:16384
	ds_read_b128 v[200:203], v165 offset:17408
	ds_read_b128 v[204:207], v165 offset:18432
	ds_read_b128 v[208:211], v165 offset:19456
	ds_read_b128 v[212:215], v165 offset:20480
	ds_read_b128 v[216:219], v165 offset:21504
	ds_read_b128 v[220:223], v165 offset:22528
	ds_read_b128 v[224:227], v165 offset:23552
	global_load_lds_dwordx4 v[152:153], off
	s_add_i32 m0, s59, 0x2000
	s_add_u32 s60, s28, 0x40000
	v_lshl_add_u64 v[228:229], s[28:29], 0, v[136:137]
	s_addc_u32 s61, s29, 0
	s_add_i32 s59, s51, s38
	global_load_lds_dwordx4 v[228:229], off
	v_lshl_add_u64 v[230:231], s[60:61], 0, v[128:129]
	s_mov_b32 m0, s59
	v_lshl_add_u64 v[232:233], s[30:31], 0, v[134:135]
	global_load_lds_dwordx4 v[230:231], off
	v_lshl_add_u64 v[230:231], s[60:61], 0, v[136:137]
	s_add_i32 m0, s59, 0x2000
	s_nop 0
	global_load_lds_dwordx4 v[230:231], off
	v_lshl_add_u64 v[230:231], s[30:31], 0, v[132:133]
	s_mov_b32 m0, s39
	s_nop 0
	global_load_lds_dwordx4 v[230:231], off
	s_mov_b32 m0, s40
	s_nop 0
	global_load_lds_dwordx4 v[232:233], off
	s_waitcnt vmcnt(8)
	s_waitcnt lgkmcnt(0)
	s_barrier
	s_setprio 1
	s_waitcnt lgkmcnt(0)
	v_mfma_f32_16x16x32_bf16 v[60:63], v[148:151], v[196:199], v[60:63]
	v_mfma_f32_16x16x32_bf16 v[56:59], v[172:175], v[196:199], v[56:59]
	v_mfma_f32_16x16x32_bf16 v[44:47], v[148:151], v[204:207], v[44:47]
	v_mfma_f32_16x16x32_bf16 v[40:43], v[172:175], v[204:207], v[40:43]
	v_mfma_f32_16x16x32_bf16 v[28:31], v[148:151], v[212:215], v[28:31]
	v_mfma_f32_16x16x32_bf16 v[24:27], v[172:175], v[212:215], v[24:27]
	v_mfma_f32_16x16x32_bf16 v[12:15], v[148:151], v[220:223], v[12:15]
	v_mfma_f32_16x16x32_bf16 v[8:11], v[172:175], v[220:223], v[8:11]
	v_mfma_f32_16x16x32_bf16 v[60:63], v[168:171], v[200:203], v[60:63]
	v_mfma_f32_16x16x32_bf16 v[56:59], v[176:179], v[200:203], v[56:59]
	v_mfma_f32_16x16x32_bf16 v[44:47], v[168:171], v[208:211], v[44:47]
	v_mfma_f32_16x16x32_bf16 v[40:43], v[176:179], v[208:211], v[40:43]
	v_mfma_f32_16x16x32_bf16 v[28:31], v[168:171], v[216:219], v[28:31]
	v_mfma_f32_16x16x32_bf16 v[24:27], v[176:179], v[216:219], v[24:27]
	v_mfma_f32_16x16x32_bf16 v[12:15], v[168:171], v[224:227], v[12:15]
	v_mfma_f32_16x16x32_bf16 v[8:11], v[176:179], v[224:227], v[8:11]
	v_mfma_f32_16x16x32_bf16 v[52:55], v[180:183], v[196:199], v[52:55]
	v_mfma_f32_16x16x32_bf16 v[48:51], v[188:191], v[196:199], v[48:51]
	v_mfma_f32_16x16x32_bf16 v[36:39], v[180:183], v[204:207], v[36:39]
	v_mfma_f32_16x16x32_bf16 v[32:35], v[188:191], v[204:207], v[32:35]
	v_mfma_f32_16x16x32_bf16 v[20:23], v[180:183], v[212:215], v[20:23]
	v_mfma_f32_16x16x32_bf16 v[16:19], v[188:191], v[212:215], v[16:19]
	v_mfma_f32_16x16x32_bf16 v[4:7], v[180:183], v[220:223], v[4:7]
	v_mfma_f32_16x16x32_bf16 v[0:3], v[188:191], v[220:223], v[0:3]
	v_mfma_f32_16x16x32_bf16 v[52:55], v[184:187], v[200:203], v[52:55]
	v_mfma_f32_16x16x32_bf16 v[48:51], v[192:195], v[200:203], v[48:51]
	v_mfma_f32_16x16x32_bf16 v[36:39], v[184:187], v[208:211], v[36:39]
	v_mfma_f32_16x16x32_bf16 v[32:35], v[192:195], v[208:211], v[32:35]
	v_mfma_f32_16x16x32_bf16 v[20:23], v[184:187], v[216:219], v[20:23]
	v_mfma_f32_16x16x32_bf16 v[16:19], v[192:195], v[216:219], v[16:19]
	v_mfma_f32_16x16x32_bf16 v[4:7], v[184:187], v[224:227], v[4:7]
	v_mfma_f32_16x16x32_bf16 v[0:3], v[192:195], v[224:227], v[0:3]
	s_setprio 0
	s_barrier
	ds_read_b128 v[148:151], v166
	ds_read_b128 v[168:171], v166 offset:1024
	ds_read_b128 v[172:175], v166 offset:2048
	ds_read_b128 v[176:179], v166 offset:3072
	ds_read_b128 v[180:183], v167
	ds_read_b128 v[184:187], v167 offset:1024
	ds_read_b128 v[188:191], v167 offset:2048
	ds_read_b128 v[192:195], v167 offset:3072
	s_add_u32 s30, s30, 0x40000
	s_addc_u32 s31, s31, 0
	s_mov_b32 m0, s41
	v_lshl_add_u64 v[234:235], s[30:31], 0, v[132:133]
	ds_read_b128 v[196:199], v165 offset:32768
	ds_read_b128 v[200:203], v165 offset:33792
	ds_read_b128 v[204:207], v165 offset:34816
	ds_read_b128 v[208:211], v165 offset:35840
	ds_read_b128 v[212:215], v165 offset:36864
	ds_read_b128 v[216:219], v165 offset:37888
	ds_read_b128 v[220:223], v165 offset:38912
	ds_read_b128 v[224:227], v165 offset:39936
	global_load_lds_dwordx4 v[234:235], off
	v_lshl_add_u64 v[234:235], s[30:31], 0, v[134:135]
	s_mov_b32 m0, s42
	s_nop 0
	global_load_lds_dwordx4 v[234:235], off
	s_waitcnt vmcnt(8)
	s_waitcnt lgkmcnt(0)
	s_barrier
	s_setprio 1
	s_waitcnt lgkmcnt(0)
	v_mfma_f32_16x16x32_bf16 v[124:127], v[148:151], v[196:199], v[124:127]
	v_mfma_f32_16x16x32_bf16 v[120:123], v[172:175], v[196:199], v[120:123]
	v_mfma_f32_16x16x32_bf16 v[108:111], v[148:151], v[204:207], v[108:111]
	v_mfma_f32_16x16x32_bf16 v[104:107], v[172:175], v[204:207], v[104:107]
	v_mfma_f32_16x16x32_bf16 v[92:95], v[148:151], v[212:215], v[92:95]
	v_mfma_f32_16x16x32_bf16 v[88:91], v[172:175], v[212:215], v[88:91]
	v_mfma_f32_16x16x32_bf16 v[76:79], v[148:151], v[220:223], v[76:79]
	v_mfma_f32_16x16x32_bf16 v[72:75], v[172:175], v[220:223], v[72:75]
	v_mfma_f32_16x16x32_bf16 v[124:127], v[168:171], v[200:203], v[124:127]
	v_mfma_f32_16x16x32_bf16 v[120:123], v[176:179], v[200:203], v[120:123]
	v_mfma_f32_16x16x32_bf16 v[108:111], v[168:171], v[208:211], v[108:111]
	v_mfma_f32_16x16x32_bf16 v[104:107], v[176:179], v[208:211], v[104:107]
	v_mfma_f32_16x16x32_bf16 v[92:95], v[168:171], v[216:219], v[92:95]
	v_mfma_f32_16x16x32_bf16 v[88:91], v[176:179], v[216:219], v[88:91]
	v_mfma_f32_16x16x32_bf16 v[76:79], v[168:171], v[224:227], v[76:79]
	v_mfma_f32_16x16x32_bf16 v[72:75], v[176:179], v[224:227], v[72:75]
	v_mfma_f32_16x16x32_bf16 v[116:119], v[180:183], v[196:199], v[116:119]
	v_mfma_f32_16x16x32_bf16 v[112:115], v[188:191], v[196:199], v[112:115]
	v_mfma_f32_16x16x32_bf16 v[100:103], v[180:183], v[204:207], v[100:103]
	v_mfma_f32_16x16x32_bf16 v[96:99], v[188:191], v[204:207], v[96:99]
	v_mfma_f32_16x16x32_bf16 v[84:87], v[180:183], v[212:215], v[84:87]
	v_mfma_f32_16x16x32_bf16 v[80:83], v[188:191], v[212:215], v[80:83]
	v_mfma_f32_16x16x32_bf16 v[68:71], v[180:183], v[220:223], v[68:71]
	v_mfma_f32_16x16x32_bf16 v[64:67], v[188:191], v[220:223], v[64:67]
	v_mfma_f32_16x16x32_bf16 v[116:119], v[184:187], v[200:203], v[116:119]
	v_mfma_f32_16x16x32_bf16 v[112:115], v[192:195], v[200:203], v[112:115]
	v_mfma_f32_16x16x32_bf16 v[100:103], v[184:187], v[208:211], v[100:103]
	v_mfma_f32_16x16x32_bf16 v[96:99], v[192:195], v[208:211], v[96:99]
	v_mfma_f32_16x16x32_bf16 v[84:87], v[184:187], v[216:219], v[84:87]
	v_mfma_f32_16x16x32_bf16 v[80:83], v[192:195], v[216:219], v[80:83]
	v_mfma_f32_16x16x32_bf16 v[68:71], v[184:187], v[224:227], v[68:71]
	v_mfma_f32_16x16x32_bf16 v[64:67], v[192:195], v[224:227], v[64:67]
	s_setprio 0
	s_barrier
	s_add_i32 s30, s54, s38
	v_lshl_add_u64 v[152:153], v[152:153], 0, s[14:15]
	s_mov_b32 m0, s30
	ds_read_b128 v[196:199], v165 offset:49152
	ds_read_b128 v[200:203], v165 offset:50176
	ds_read_b128 v[204:207], v165 offset:51200
	ds_read_b128 v[208:211], v165 offset:52224
	ds_read_b128 v[212:215], v165 offset:53248
	ds_read_b128 v[216:219], v165 offset:54272
	ds_read_b128 v[220:223], v165 offset:55296
	ds_read_b128 v[224:227], v165 offset:56320
	global_load_lds_dwordx4 v[152:153], off
	s_add_i32 m0, s30, 0x2000
	s_add_u32 s28, s28, 0x40080
	v_lshl_add_u64 v[152:153], v[228:229], 0, s[14:15]
	s_addc_u32 s29, s29, 0
	s_add_i32 s30, s55, s38
	global_load_lds_dwordx4 v[152:153], off
	v_lshl_add_u64 v[152:153], s[28:29], 0, v[128:129]
	s_mov_b32 m0, s30
	s_nop 0
	global_load_lds_dwordx4 v[152:153], off
	v_lshl_add_u64 v[152:153], s[28:29], 0, v[136:137]
	s_add_i32 m0, s30, 0x2000
	s_nop 0
	global_load_lds_dwordx4 v[152:153], off
	v_lshl_add_u64 v[152:153], v[230:231], 0, s[14:15]
	s_mov_b32 m0, s46
	s_nop 0
	global_load_lds_dwordx4 v[152:153], off
	v_lshl_add_u64 v[152:153], v[232:233], 0, s[14:15]
	s_mov_b32 m0, s47
	s_nop 0
	global_load_lds_dwordx4 v[152:153], off
	s_waitcnt vmcnt(8)
	s_waitcnt lgkmcnt(0)
	s_barrier
	s_setprio 1
	s_waitcnt lgkmcnt(0)
	v_mfma_f32_16x16x32_bf16 v[60:63], v[148:151], v[196:199], v[60:63]
	v_mfma_f32_16x16x32_bf16 v[56:59], v[172:175], v[196:199], v[56:59]
	v_mfma_f32_16x16x32_bf16 v[44:47], v[148:151], v[204:207], v[44:47]
	v_mfma_f32_16x16x32_bf16 v[40:43], v[172:175], v[204:207], v[40:43]
	v_mfma_f32_16x16x32_bf16 v[28:31], v[148:151], v[212:215], v[28:31]
	v_mfma_f32_16x16x32_bf16 v[24:27], v[172:175], v[212:215], v[24:27]
	v_mfma_f32_16x16x32_bf16 v[12:15], v[148:151], v[220:223], v[12:15]
	v_mfma_f32_16x16x32_bf16 v[8:11], v[172:175], v[220:223], v[8:11]
	v_mfma_f32_16x16x32_bf16 v[60:63], v[168:171], v[200:203], v[60:63]
	v_mfma_f32_16x16x32_bf16 v[56:59], v[176:179], v[200:203], v[56:59]
	v_mfma_f32_16x16x32_bf16 v[44:47], v[168:171], v[208:211], v[44:47]
	v_mfma_f32_16x16x32_bf16 v[40:43], v[176:179], v[208:211], v[40:43]
	v_mfma_f32_16x16x32_bf16 v[28:31], v[168:171], v[216:219], v[28:31]
	v_mfma_f32_16x16x32_bf16 v[24:27], v[176:179], v[216:219], v[24:27]
	v_mfma_f32_16x16x32_bf16 v[12:15], v[168:171], v[224:227], v[12:15]
	v_mfma_f32_16x16x32_bf16 v[8:11], v[176:179], v[224:227], v[8:11]
	v_mfma_f32_16x16x32_bf16 v[52:55], v[180:183], v[196:199], v[52:55]
	v_mfma_f32_16x16x32_bf16 v[48:51], v[188:191], v[196:199], v[48:51]
	v_mfma_f32_16x16x32_bf16 v[36:39], v[180:183], v[204:207], v[36:39]
	v_mfma_f32_16x16x32_bf16 v[32:35], v[188:191], v[204:207], v[32:35]
	v_mfma_f32_16x16x32_bf16 v[20:23], v[180:183], v[212:215], v[20:23]
	v_mfma_f32_16x16x32_bf16 v[16:19], v[188:191], v[212:215], v[16:19]
	v_mfma_f32_16x16x32_bf16 v[4:7], v[180:183], v[220:223], v[4:7]
	v_mfma_f32_16x16x32_bf16 v[0:3], v[188:191], v[220:223], v[0:3]
	v_mfma_f32_16x16x32_bf16 v[52:55], v[184:187], v[200:203], v[52:55]
	v_mfma_f32_16x16x32_bf16 v[48:51], v[192:195], v[200:203], v[48:51]
	v_mfma_f32_16x16x32_bf16 v[36:39], v[184:187], v[208:211], v[36:39]
	v_mfma_f32_16x16x32_bf16 v[32:35], v[192:195], v[208:211], v[32:35]
	v_mfma_f32_16x16x32_bf16 v[20:23], v[184:187], v[216:219], v[20:23]
	v_mfma_f32_16x16x32_bf16 v[16:19], v[192:195], v[216:219], v[16:19]
	v_mfma_f32_16x16x32_bf16 v[4:7], v[184:187], v[224:227], v[4:7]
	v_mfma_f32_16x16x32_bf16 v[0:3], v[192:195], v[224:227], v[0:3]
	s_setprio 0
	s_barrier
	s_add_i32 s58, s58, 2
	s_add_u32 s26, s26, 0x100
	s_addc_u32 s27, s27, 0
	s_add_u32 s56, s56, 0x100
	s_addc_u32 s57, s57, 0
	s_cmp_gt_u32 s58, 13
	s_cbranch_scc0 .LBB0_306
	s_and_b64 vcc, exec, s[16:17]
	s_cbranch_vccz .LBB0_309
	s_barrier

.LBB0_762:
	ds_read_b128 v[156:159], v146
	ds_read_b128 v[160:163], v146 offset:1024
	ds_read_b128 v[164:167], v146 offset:2048
	ds_read_b128 v[168:171], v146 offset:3072
	ds_read_b128 v[172:175], v147
	ds_read_b128 v[176:179], v147 offset:1024
	ds_read_b128 v[180:183], v147 offset:2048
	ds_read_b128 v[184:187], v147 offset:3072
	s_add_u32 s26, s24, 0xfffc0080
	s_addc_u32 s27, s25, -1
	s_cmp_eq_u32 s53, 12
	s_cselect_b32 s29, s13, s27
	s_cselect_b32 s28, s49, s26
	s_cselect_b32 s27, s15, s52
	s_cselect_b32 s26, s50, s51
	v_lshl_add_u64 v[152:153], s[24:25], 0, v[136:137]
	s_add_i32 m0, s19, 0xc000
	ds_read_b128 v[188:191], v148
	ds_read_b128 v[192:195], v148 offset:1024
	ds_read_b128 v[196:199], v148 offset:2048
	ds_read_b128 v[200:203], v148 offset:3072
	ds_read_b128 v[204:207], v148 offset:4096
	ds_read_b128 v[208:211], v148 offset:5120
	ds_read_b128 v[212:215], v148 offset:6144
	ds_read_b128 v[216:219], v148 offset:7168
	global_load_lds_dwordx4 v[152:153], off
	v_lshl_add_u64 v[152:153], s[24:25], 0, v[138:139]
	s_add_i32 m0, s19, 0xe000
	s_nop 0
	global_load_lds_dwordx4 v[152:153], off
	s_waitcnt vmcnt(8)
	s_waitcnt lgkmcnt(0)
	s_barrier
	s_setprio 1
	s_waitcnt lgkmcnt(0)
	v_mfma_f32_16x16x32_bf16 v[124:127], v[156:159], v[188:191], v[124:127]
	v_mfma_f32_16x16x32_bf16 v[120:123], v[164:167], v[188:191], v[120:123]
	v_mfma_f32_16x16x32_bf16 v[116:119], v[156:159], v[196:199], v[116:119]
	v_mfma_f32_16x16x32_bf16 v[112:115], v[164:167], v[196:199], v[112:115]
	v_mfma_f32_16x16x32_bf16 v[100:103], v[156:159], v[204:207], v[100:103]
	v_mfma_f32_16x16x32_bf16 v[96:99], v[164:167], v[204:207], v[96:99]
	v_mfma_f32_16x16x32_bf16 v[84:87], v[156:159], v[212:215], v[84:87]
	v_mfma_f32_16x16x32_bf16 v[80:83], v[164:167], v[212:215], v[80:83]
	v_mfma_f32_16x16x32_bf16 v[124:127], v[160:163], v[192:195], v[124:127]
	v_mfma_f32_16x16x32_bf16 v[120:123], v[168:171], v[192:195], v[120:123]
	v_mfma_f32_16x16x32_bf16 v[116:119], v[160:163], v[200:203], v[116:119]
	v_mfma_f32_16x16x32_bf16 v[112:115], v[168:171], v[200:203], v[112:115]
	v_mfma_f32_16x16x32_bf16 v[100:103], v[160:163], v[208:211], v[100:103]
	v_mfma_f32_16x16x32_bf16 v[96:99], v[168:171], v[208:211], v[96:99]
	v_mfma_f32_16x16x32_bf16 v[84:87], v[160:163], v[216:219], v[84:87]
	v_mfma_f32_16x16x32_bf16 v[80:83], v[168:171], v[216:219], v[80:83]
	v_mfma_f32_16x16x32_bf16 v[108:111], v[172:175], v[188:191], v[108:111]
	v_mfma_f32_16x16x32_bf16 v[104:107], v[180:183], v[188:191], v[104:107]
	v_mfma_f32_16x16x32_bf16 v[92:95], v[172:175], v[196:199], v[92:95]
	v_mfma_f32_16x16x32_bf16 v[88:91], v[180:183], v[196:199], v[88:91]
	v_mfma_f32_16x16x32_bf16 v[76:79], v[172:175], v[204:207], v[76:79]
	v_mfma_f32_16x16x32_bf16 v[72:75], v[180:183], v[204:207], v[72:75]
	v_mfma_f32_16x16x32_bf16 v[68:71], v[172:175], v[212:215], v[68:71]
	v_mfma_f32_16x16x32_bf16 v[64:67], v[180:183], v[212:215], v[64:67]
	v_mfma_f32_16x16x32_bf16 v[108:111], v[176:179], v[192:195], v[108:111]
	v_mfma_f32_16x16x32_bf16 v[104:107], v[184:187], v[192:195], v[104:107]
	v_mfma_f32_16x16x32_bf16 v[92:95], v[176:179], v[200:203], v[92:95]
	v_mfma_f32_16x16x32_bf16 v[88:91], v[184:187], v[200:203], v[88:91]
	v_mfma_f32_16x16x32_bf16 v[76:79], v[176:179], v[208:211], v[76:79]
	v_mfma_f32_16x16x32_bf16 v[72:75], v[184:187], v[208:211], v[72:75]
	v_mfma_f32_16x16x32_bf16 v[68:71], v[176:179], v[216:219], v[68:71]
	v_mfma_f32_16x16x32_bf16 v[64:67], v[184:187], v[216:219], v[64:67]
	s_setprio 0
	s_barrier
	s_add_i32 s54, s45, s17
	v_lshl_add_u64 v[152:153], s[26:27], 0, v[128:129]
	s_mov_b32 m0, s54
	ds_read_b128 v[188:191], v148 offset:16384
	ds_read_b128 v[192:195], v148 offset:17408
	ds_read_b128 v[196:199], v148 offset:18432
	ds_read_b128 v[200:203], v148 offset:19456
	ds_read_b128 v[204:207], v148 offset:20480
	ds_read_b128 v[208:211], v148 offset:21504
	ds_read_b128 v[212:215], v148 offset:22528
	ds_read_b128 v[216:219], v148 offset:23552
	global_load_lds_dwordx4 v[152:153], off
	s_add_i32 m0, s54, 0x2000
	s_add_u32 s54, s26, 0x40000
	v_lshl_add_u64 v[220:221], s[26:27], 0, v[130:131]
	s_addc_u32 s55, s27, 0
	s_add_i32 s56, s46, s17
	global_load_lds_dwordx4 v[220:221], off
	v_lshl_add_u64 v[222:223], s[54:55], 0, v[128:129]
	s_mov_b32 m0, s56
	v_lshl_add_u64 v[224:225], s[28:29], 0, v[132:133]
	global_load_lds_dwordx4 v[222:223], off
	v_lshl_add_u64 v[222:223], s[54:55], 0, v[130:131]
	s_add_i32 m0, s56, 0x2000
	s_nop 0
	global_load_lds_dwordx4 v[222:223], off
	v_lshl_add_u64 v[222:223], s[28:29], 0, v[134:135]
	s_mov_b32 m0, s19
	s_nop 0
	global_load_lds_dwordx4 v[222:223], off
	s_mov_b32 m0, s37
	s_nop 0
	global_load_lds_dwordx4 v[224:225], off
	s_waitcnt vmcnt(8)
	s_waitcnt lgkmcnt(0)
	s_barrier
	s_setprio 1
	s_waitcnt lgkmcnt(0)
	v_mfma_f32_16x16x32_bf16 v[60:63], v[156:159], v[188:191], v[60:63]
	v_mfma_f32_16x16x32_bf16 v[56:59], v[164:167], v[188:191], v[56:59]
	v_mfma_f32_16x16x32_bf16 v[52:55], v[156:159], v[196:199], v[52:55]
	v_mfma_f32_16x16x32_bf16 v[48:51], v[164:167], v[196:199], v[48:51]
	v_mfma_f32_16x16x32_bf16 v[36:39], v[156:159], v[204:207], v[36:39]
	v_mfma_f32_16x16x32_bf16 v[32:35], v[164:167], v[204:207], v[32:35]
	v_mfma_f32_16x16x32_bf16 v[20:23], v[156:159], v[212:215], v[20:23]
	v_mfma_f32_16x16x32_bf16 v[16:19], v[164:167], v[212:215], v[16:19]
	v_mfma_f32_16x16x32_bf16 v[60:63], v[160:163], v[192:195], v[60:63]
	v_mfma_f32_16x16x32_bf16 v[56:59], v[168:171], v[192:195], v[56:59]
	v_mfma_f32_16x16x32_bf16 v[52:55], v[160:163], v[200:203], v[52:55]
	v_mfma_f32_16x16x32_bf16 v[48:51], v[168:171], v[200:203], v[48:51]
	v_mfma_f32_16x16x32_bf16 v[36:39], v[160:163], v[208:211], v[36:39]
	v_mfma_f32_16x16x32_bf16 v[32:35], v[168:171], v[208:211], v[32:35]
	v_mfma_f32_16x16x32_bf16 v[20:23], v[160:163], v[216:219], v[20:23]
	v_mfma_f32_16x16x32_bf16 v[16:19], v[168:171], v[216:219], v[16:19]
	v_mfma_f32_16x16x32_bf16 v[44:47], v[172:175], v[188:191], v[44:47]
	v_mfma_f32_16x16x32_bf16 v[40:43], v[180:183], v[188:191], v[40:43]
	v_mfma_f32_16x16x32_bf16 v[28:31], v[172:175], v[196:199], v[28:31]
	v_mfma_f32_16x16x32_bf16 v[24:27], v[180:183], v[196:199], v[24:27]
	v_mfma_f32_16x16x32_bf16 v[12:15], v[172:175], v[204:207], v[12:15]
	v_mfma_f32_16x16x32_bf16 v[8:11], v[180:183], v[204:207], v[8:11]
	v_mfma_f32_16x16x32_bf16 v[4:7], v[172:175], v[212:215], v[4:7]
	v_mfma_f32_16x16x32_bf16 v[0:3], v[180:183], v[212:215], v[0:3]
	v_mfma_f32_16x16x32_bf16 v[44:47], v[176:179], v[192:195], v[44:47]
	v_mfma_f32_16x16x32_bf16 v[40:43], v[184:187], v[192:195], v[40:43]
	v_mfma_f32_16x16x32_bf16 v[28:31], v[176:179], v[200:203], v[28:31]
	v_mfma_f32_16x16x32_bf16 v[24:27], v[184:187], v[200:203], v[24:27]
	v_mfma_f32_16x16x32_bf16 v[12:15], v[176:179], v[208:211], v[12:15]
	v_mfma_f32_16x16x32_bf16 v[8:11], v[184:187], v[208:211], v[8:11]
	v_mfma_f32_16x16x32_bf16 v[4:7], v[176:179], v[216:219], v[4:7]
	v_mfma_f32_16x16x32_bf16 v[0:3], v[184:187], v[216:219], v[0:3]
	s_setprio 0
	s_barrier
	ds_read_b128 v[156:159], v149
	ds_read_b128 v[160:163], v149 offset:1024
	ds_read_b128 v[164:167], v149 offset:2048
	ds_read_b128 v[168:171], v149 offset:3072
	ds_read_b128 v[172:175], v150
	ds_read_b128 v[176:179], v150 offset:1024
	ds_read_b128 v[180:183], v150 offset:2048
	ds_read_b128 v[184:187], v150 offset:3072
	s_add_u32 s28, s28, 0x40000
	s_addc_u32 s29, s29, 0
	s_mov_b32 m0, s38
	v_lshl_add_u64 v[226:227], s[28:29], 0, v[134:135]
	ds_read_b128 v[188:191], v148 offset:32768
	ds_read_b128 v[192:195], v148 offset:33792
	ds_read_b128 v[196:199], v148 offset:34816
	ds_read_b128 v[200:203], v148 offset:35840
	ds_read_b128 v[204:207], v148 offset:36864
	ds_read_b128 v[208:211], v148 offset:37888
	ds_read_b128 v[212:215], v148 offset:38912
	ds_read_b128 v[216:219], v148 offset:39936
	global_load_lds_dwordx4 v[226:227], off
	v_lshl_add_u64 v[226:227], s[28:29], 0, v[132:133]
	s_mov_b32 m0, s39
	s_nop 0
	global_load_lds_dwordx4 v[226:227], off
	s_waitcnt vmcnt(8)
	s_waitcnt lgkmcnt(0)
	s_barrier
	s_setprio 1
	s_waitcnt lgkmcnt(0)
	v_mfma_f32_16x16x32_bf16 v[124:127], v[156:159], v[188:191], v[124:127]
	v_mfma_f32_16x16x32_bf16 v[120:123], v[164:167], v[188:191], v[120:123]
	v_mfma_f32_16x16x32_bf16 v[116:119], v[156:159], v[196:199], v[116:119]
	v_mfma_f32_16x16x32_bf16 v[112:115], v[164:167], v[196:199], v[112:115]
	v_mfma_f32_16x16x32_bf16 v[100:103], v[156:159], v[204:207], v[100:103]
	v_mfma_f32_16x16x32_bf16 v[96:99], v[164:167], v[204:207], v[96:99]
	v_mfma_f32_16x16x32_bf16 v[84:87], v[156:159], v[212:215], v[84:87]
	v_mfma_f32_16x16x32_bf16 v[80:83], v[164:167], v[212:215], v[80:83]
	v_mfma_f32_16x16x32_bf16 v[124:127], v[160:163], v[192:195], v[124:127]
	v_mfma_f32_16x16x32_bf16 v[120:123], v[168:171], v[192:195], v[120:123]
	v_mfma_f32_16x16x32_bf16 v[116:119], v[160:163], v[200:203], v[116:119]
	v_mfma_f32_16x16x32_bf16 v[112:115], v[168:171], v[200:203], v[112:115]
	v_mfma_f32_16x16x32_bf16 v[100:103], v[160:163], v[208:211], v[100:103]
	v_mfma_f32_16x16x32_bf16 v[96:99], v[168:171], v[208:211], v[96:99]
	v_mfma_f32_16x16x32_bf16 v[84:87], v[160:163], v[216:219], v[84:87]
	v_mfma_f32_16x16x32_bf16 v[80:83], v[168:171], v[216:219], v[80:83]
	v_mfma_f32_16x16x32_bf16 v[108:111], v[172:175], v[188:191], v[108:111]
	v_mfma_f32_16x16x32_bf16 v[104:107], v[180:183], v[188:191], v[104:107]
	v_mfma_f32_16x16x32_bf16 v[92:95], v[172:175], v[196:199], v[92:95]
	v_mfma_f32_16x16x32_bf16 v[88:91], v[180:183], v[196:199], v[88:91]
	v_mfma_f32_16x16x32_bf16 v[76:79], v[172:175], v[204:207], v[76:79]
	v_mfma_f32_16x16x32_bf16 v[72:75], v[180:183], v[204:207], v[72:75]
	v_mfma_f32_16x16x32_bf16 v[68:71], v[172:175], v[212:215], v[68:71]
	v_mfma_f32_16x16x32_bf16 v[64:67], v[180:183], v[212:215], v[64:67]
	v_mfma_f32_16x16x32_bf16 v[108:111], v[176:179], v[192:195], v[108:111]
	v_mfma_f32_16x16x32_bf16 v[104:107], v[184:187], v[192:195], v[104:107]
	v_mfma_f32_16x16x32_bf16 v[92:95], v[176:179], v[200:203], v[92:95]
	v_mfma_f32_16x16x32_bf16 v[88:91], v[184:187], v[200:203], v[88:91]
	v_mfma_f32_16x16x32_bf16 v[76:79], v[176:179], v[208:211], v[76:79]
	v_mfma_f32_16x16x32_bf16 v[72:75], v[184:187], v[208:211], v[72:75]
	v_mfma_f32_16x16x32_bf16 v[68:71], v[176:179], v[216:219], v[68:71]
	v_mfma_f32_16x16x32_bf16 v[64:67], v[184:187], v[216:219], v[64:67]
	s_setprio 0
	s_barrier
	s_add_i32 s28, s47, s17
	v_lshl_add_u64 v[152:153], v[152:153], 0, s[8:9]
	s_mov_b32 m0, s28
	ds_read_b128 v[188:191], v148 offset:49152
	ds_read_b128 v[192:195], v148 offset:50176
	ds_read_b128 v[196:199], v148 offset:51200
	ds_read_b128 v[200:203], v148 offset:52224
	ds_read_b128 v[204:207], v148 offset:53248
	ds_read_b128 v[208:211], v148 offset:54272
	ds_read_b128 v[212:215], v148 offset:55296
	ds_read_b128 v[216:219], v148 offset:56320
	global_load_lds_dwordx4 v[152:153], off
	s_add_i32 m0, s28, 0x2000
	s_add_u32 s26, s26, 0x40080
	v_lshl_add_u64 v[152:153], v[220:221], 0, s[8:9]
	s_addc_u32 s27, s27, 0
	s_add_i32 s28, s48, s17
	global_load_lds_dwordx4 v[152:153], off
	v_lshl_add_u64 v[152:153], s[26:27], 0, v[128:129]
	s_mov_b32 m0, s28
	s_nop 0
	global_load_lds_dwordx4 v[152:153], off
	v_lshl_add_u64 v[152:153], s[26:27], 0, v[130:131]
	s_add_i32 m0, s28, 0x2000
	s_nop 0
	global_load_lds_dwordx4 v[152:153], off
	v_lshl_add_u64 v[152:153], v[222:223], 0, s[8:9]
	s_mov_b32 m0, s40
	s_nop 0
	global_load_lds_dwordx4 v[152:153], off
	v_lshl_add_u64 v[152:153], v[224:225], 0, s[8:9]
	s_mov_b32 m0, s41
	s_nop 0
	global_load_lds_dwordx4 v[152:153], off
	s_waitcnt vmcnt(8)
	s_waitcnt lgkmcnt(0)
	s_barrier
	s_setprio 1
	s_waitcnt lgkmcnt(0)
	v_mfma_f32_16x16x32_bf16 v[60:63], v[156:159], v[188:191], v[60:63]
	v_mfma_f32_16x16x32_bf16 v[56:59], v[164:167], v[188:191], v[56:59]
	v_mfma_f32_16x16x32_bf16 v[52:55], v[156:159], v[196:199], v[52:55]
	v_mfma_f32_16x16x32_bf16 v[48:51], v[164:167], v[196:199], v[48:51]
	v_mfma_f32_16x16x32_bf16 v[36:39], v[156:159], v[204:207], v[36:39]
	v_mfma_f32_16x16x32_bf16 v[32:35], v[164:167], v[204:207], v[32:35]
	v_mfma_f32_16x16x32_bf16 v[20:23], v[156:159], v[212:215], v[20:23]
	v_mfma_f32_16x16x32_bf16 v[16:19], v[164:167], v[212:215], v[16:19]
	v_mfma_f32_16x16x32_bf16 v[60:63], v[160:163], v[192:195], v[60:63]
	v_mfma_f32_16x16x32_bf16 v[56:59], v[168:171], v[192:195], v[56:59]
	v_mfma_f32_16x16x32_bf16 v[52:55], v[160:163], v[200:203], v[52:55]
	v_mfma_f32_16x16x32_bf16 v[48:51], v[168:171], v[200:203], v[48:51]
	v_mfma_f32_16x16x32_bf16 v[36:39], v[160:163], v[208:211], v[36:39]
	v_mfma_f32_16x16x32_bf16 v[32:35], v[168:171], v[208:211], v[32:35]
	v_mfma_f32_16x16x32_bf16 v[20:23], v[160:163], v[216:219], v[20:23]
	v_mfma_f32_16x16x32_bf16 v[16:19], v[168:171], v[216:219], v[16:19]
	v_mfma_f32_16x16x32_bf16 v[44:47], v[172:175], v[188:191], v[44:47]
	v_mfma_f32_16x16x32_bf16 v[40:43], v[180:183], v[188:191], v[40:43]
	v_mfma_f32_16x16x32_bf16 v[28:31], v[172:175], v[196:199], v[28:31]
	v_mfma_f32_16x16x32_bf16 v[24:27], v[180:183], v[196:199], v[24:27]
	v_mfma_f32_16x16x32_bf16 v[12:15], v[172:175], v[204:207], v[12:15]
	v_mfma_f32_16x16x32_bf16 v[8:11], v[180:183], v[204:207], v[8:11]
	v_mfma_f32_16x16x32_bf16 v[4:7], v[172:175], v[212:215], v[4:7]
	v_mfma_f32_16x16x32_bf16 v[0:3], v[180:183], v[212:215], v[0:3]
	v_mfma_f32_16x16x32_bf16 v[44:47], v[176:179], v[192:195], v[44:47]
	v_mfma_f32_16x16x32_bf16 v[40:43], v[184:187], v[192:195], v[40:43]
	v_mfma_f32_16x16x32_bf16 v[28:31], v[176:179], v[200:203], v[28:31]
	v_mfma_f32_16x16x32_bf16 v[24:27], v[184:187], v[200:203], v[24:27]
	v_mfma_f32_16x16x32_bf16 v[12:15], v[176:179], v[208:211], v[12:15]
	v_mfma_f32_16x16x32_bf16 v[8:11], v[184:187], v[208:211], v[8:11]
	v_mfma_f32_16x16x32_bf16 v[4:7], v[176:179], v[216:219], v[4:7]
	v_mfma_f32_16x16x32_bf16 v[0:3], v[184:187], v[216:219], v[0:3]
	s_setprio 0
	s_barrier
	s_add_i32 s53, s53, 2
	s_add_u32 s24, s24, 0x100
	s_addc_u32 s25, s25, 0
	s_add_u32 s51, s51, 0x100
	s_addc_u32 s52, s52, 0
	s_cmp_gt_u32 s53, 13
	s_cbranch_scc0 .LBB0_762
	s_and_b64 vcc, exec, s[10:11]
	s_cbranch_vccz .LBB0_765
	s_barrier

.LBB0_842:
	ds_read_b128 v[148:151], v142
	ds_read_b128 v[156:159], v142 offset:1024
	ds_read_b128 v[160:163], v142 offset:2048
	ds_read_b128 v[164:167], v142 offset:3072
	ds_read_b128 v[168:171], v143
	ds_read_b128 v[172:175], v143 offset:1024
	ds_read_b128 v[176:179], v143 offset:2048
	ds_read_b128 v[180:183], v143 offset:3072
	s_add_u32 s40, s38, 0xfffc0080
	s_addc_u32 s41, s39, -1
	s_cmp_eq_u32 s64, 12
	s_cselect_b32 s43, s23, s41
	s_cselect_b32 s42, s27, s40
	s_cselect_b32 s41, s25, s63
	s_cselect_b32 s40, s61, s62
	v_lshl_add_u64 v[152:153], s[38:39], 0, v[136:137]
	s_add_i32 m0, s29, 0xc000
	ds_read_b128 v[184:187], v144
	ds_read_b128 v[188:191], v144 offset:1024
	ds_read_b128 v[192:195], v144 offset:2048
	ds_read_b128 v[196:199], v144 offset:3072
	ds_read_b128 v[200:203], v144 offset:4096
	ds_read_b128 v[204:207], v144 offset:5120
	ds_read_b128 v[208:211], v144 offset:6144
	ds_read_b128 v[212:215], v144 offset:7168
	global_load_lds_dwordx4 v[152:153], off
	v_lshl_add_u64 v[152:153], s[38:39], 0, v[138:139]
	s_add_i32 m0, s29, 0xe000
	s_nop 0
	global_load_lds_dwordx4 v[152:153], off
	s_waitcnt vmcnt(8)
	s_waitcnt lgkmcnt(0)
	s_barrier
	s_setprio 1
	s_waitcnt lgkmcnt(0)
	v_mfma_f32_16x16x32_bf16 v[124:127], v[148:151], v[184:187], v[124:127]
	v_mfma_f32_16x16x32_bf16 v[120:123], v[160:163], v[184:187], v[120:123]
	v_mfma_f32_16x16x32_bf16 v[116:119], v[148:151], v[192:195], v[116:119]
	v_mfma_f32_16x16x32_bf16 v[112:115], v[160:163], v[192:195], v[112:115]
	v_mfma_f32_16x16x32_bf16 v[100:103], v[148:151], v[200:203], v[100:103]
	v_mfma_f32_16x16x32_bf16 v[96:99], v[160:163], v[200:203], v[96:99]
	v_mfma_f32_16x16x32_bf16 v[84:87], v[148:151], v[208:211], v[84:87]
	v_mfma_f32_16x16x32_bf16 v[80:83], v[160:163], v[208:211], v[80:83]
	v_mfma_f32_16x16x32_bf16 v[124:127], v[156:159], v[188:191], v[124:127]
	v_mfma_f32_16x16x32_bf16 v[120:123], v[164:167], v[188:191], v[120:123]
	v_mfma_f32_16x16x32_bf16 v[116:119], v[156:159], v[196:199], v[116:119]
	v_mfma_f32_16x16x32_bf16 v[112:115], v[164:167], v[196:199], v[112:115]
	v_mfma_f32_16x16x32_bf16 v[100:103], v[156:159], v[204:207], v[100:103]
	v_mfma_f32_16x16x32_bf16 v[96:99], v[164:167], v[204:207], v[96:99]
	v_mfma_f32_16x16x32_bf16 v[84:87], v[156:159], v[212:215], v[84:87]
	v_mfma_f32_16x16x32_bf16 v[80:83], v[164:167], v[212:215], v[80:83]
	v_mfma_f32_16x16x32_bf16 v[108:111], v[168:171], v[184:187], v[108:111]
	v_mfma_f32_16x16x32_bf16 v[104:107], v[176:179], v[184:187], v[104:107]
	v_mfma_f32_16x16x32_bf16 v[92:95], v[168:171], v[192:195], v[92:95]
	v_mfma_f32_16x16x32_bf16 v[88:91], v[176:179], v[192:195], v[88:91]
	v_mfma_f32_16x16x32_bf16 v[76:79], v[168:171], v[200:203], v[76:79]
	v_mfma_f32_16x16x32_bf16 v[72:75], v[176:179], v[200:203], v[72:75]
	v_mfma_f32_16x16x32_bf16 v[68:71], v[168:171], v[208:211], v[68:71]
	v_mfma_f32_16x16x32_bf16 v[64:67], v[176:179], v[208:211], v[64:67]
	v_mfma_f32_16x16x32_bf16 v[108:111], v[172:175], v[188:191], v[108:111]
	v_mfma_f32_16x16x32_bf16 v[104:107], v[180:183], v[188:191], v[104:107]
	v_mfma_f32_16x16x32_bf16 v[92:95], v[172:175], v[196:199], v[92:95]
	v_mfma_f32_16x16x32_bf16 v[88:91], v[180:183], v[196:199], v[88:91]
	v_mfma_f32_16x16x32_bf16 v[76:79], v[172:175], v[204:207], v[76:79]
	v_mfma_f32_16x16x32_bf16 v[72:75], v[180:183], v[204:207], v[72:75]
	v_mfma_f32_16x16x32_bf16 v[68:71], v[172:175], v[212:215], v[68:71]
	v_mfma_f32_16x16x32_bf16 v[64:67], v[180:183], v[212:215], v[64:67]
	s_setprio 0
	s_barrier
	s_add_i32 s65, s57, s50
	v_lshl_add_u64 v[152:153], s[40:41], 0, v[132:133]
	s_mov_b32 m0, s65
	ds_read_b128 v[184:187], v144 offset:16384
	ds_read_b128 v[188:191], v144 offset:17408
	ds_read_b128 v[192:195], v144 offset:18432
	ds_read_b128 v[196:199], v144 offset:19456
	ds_read_b128 v[200:203], v144 offset:20480
	ds_read_b128 v[204:207], v144 offset:21504
	ds_read_b128 v[208:211], v144 offset:22528
	ds_read_b128 v[212:215], v144 offset:23552
	global_load_lds_dwordx4 v[152:153], off
	s_add_i32 m0, s65, 0x2000
	s_add_u32 s66, s40, 0x40000
	v_lshl_add_u64 v[216:217], s[40:41], 0, v[128:129]
	s_addc_u32 s67, s41, 0
	s_add_i32 s65, s58, s50
	global_load_lds_dwordx4 v[216:217], off
	v_lshl_add_u64 v[218:219], s[66:67], 0, v[132:133]
	s_mov_b32 m0, s65
	v_lshl_add_u64 v[220:221], s[42:43], 0, v[130:131]
	global_load_lds_dwordx4 v[218:219], off
	v_lshl_add_u64 v[218:219], s[66:67], 0, v[128:129]
	s_add_i32 m0, s65, 0x2000
	s_nop 0
	global_load_lds_dwordx4 v[218:219], off
	v_lshl_add_u64 v[218:219], s[42:43], 0, v[134:135]
	s_mov_b32 m0, s29
	s_nop 0
	global_load_lds_dwordx4 v[218:219], off
	s_mov_b32 m0, s52
	s_nop 0
	global_load_lds_dwordx4 v[220:221], off
	s_waitcnt vmcnt(8)
	s_waitcnt lgkmcnt(0)
	s_barrier
	s_setprio 1
	s_waitcnt lgkmcnt(0)
	v_mfma_f32_16x16x32_bf16 v[60:63], v[148:151], v[184:187], v[60:63]
	v_mfma_f32_16x16x32_bf16 v[56:59], v[160:163], v[184:187], v[56:59]
	v_mfma_f32_16x16x32_bf16 v[52:55], v[148:151], v[192:195], v[52:55]
	v_mfma_f32_16x16x32_bf16 v[48:51], v[160:163], v[192:195], v[48:51]
	v_mfma_f32_16x16x32_bf16 v[36:39], v[148:151], v[200:203], v[36:39]
	v_mfma_f32_16x16x32_bf16 v[32:35], v[160:163], v[200:203], v[32:35]
	v_mfma_f32_16x16x32_bf16 v[20:23], v[148:151], v[208:211], v[20:23]
	v_mfma_f32_16x16x32_bf16 v[16:19], v[160:163], v[208:211], v[16:19]
	v_mfma_f32_16x16x32_bf16 v[60:63], v[156:159], v[188:191], v[60:63]
	v_mfma_f32_16x16x32_bf16 v[56:59], v[164:167], v[188:191], v[56:59]
	v_mfma_f32_16x16x32_bf16 v[52:55], v[156:159], v[196:199], v[52:55]
	v_mfma_f32_16x16x32_bf16 v[48:51], v[164:167], v[196:199], v[48:51]
	v_mfma_f32_16x16x32_bf16 v[36:39], v[156:159], v[204:207], v[36:39]
	v_mfma_f32_16x16x32_bf16 v[32:35], v[164:167], v[204:207], v[32:35]
	v_mfma_f32_16x16x32_bf16 v[20:23], v[156:159], v[212:215], v[20:23]
	v_mfma_f32_16x16x32_bf16 v[16:19], v[164:167], v[212:215], v[16:19]
	v_mfma_f32_16x16x32_bf16 v[44:47], v[168:171], v[184:187], v[44:47]
	v_mfma_f32_16x16x32_bf16 v[40:43], v[176:179], v[184:187], v[40:43]
	v_mfma_f32_16x16x32_bf16 v[28:31], v[168:171], v[192:195], v[28:31]
	v_mfma_f32_16x16x32_bf16 v[24:27], v[176:179], v[192:195], v[24:27]
	v_mfma_f32_16x16x32_bf16 v[12:15], v[168:171], v[200:203], v[12:15]
	v_mfma_f32_16x16x32_bf16 v[8:11], v[176:179], v[200:203], v[8:11]
	v_mfma_f32_16x16x32_bf16 v[4:7], v[168:171], v[208:211], v[4:7]
	v_mfma_f32_16x16x32_bf16 v[0:3], v[176:179], v[208:211], v[0:3]
	v_mfma_f32_16x16x32_bf16 v[44:47], v[172:175], v[188:191], v[44:47]
	v_mfma_f32_16x16x32_bf16 v[40:43], v[180:183], v[188:191], v[40:43]
	v_mfma_f32_16x16x32_bf16 v[28:31], v[172:175], v[196:199], v[28:31]
	v_mfma_f32_16x16x32_bf16 v[24:27], v[180:183], v[196:199], v[24:27]
	v_mfma_f32_16x16x32_bf16 v[12:15], v[172:175], v[204:207], v[12:15]
	v_mfma_f32_16x16x32_bf16 v[8:11], v[180:183], v[204:207], v[8:11]
	v_mfma_f32_16x16x32_bf16 v[4:7], v[172:175], v[212:215], v[4:7]
	v_mfma_f32_16x16x32_bf16 v[0:3], v[180:183], v[212:215], v[0:3]
	s_setprio 0
	s_barrier
	ds_read_b128 v[148:151], v145
	ds_read_b128 v[156:159], v145 offset:1024
	ds_read_b128 v[160:163], v145 offset:2048
	ds_read_b128 v[164:167], v145 offset:3072
	ds_read_b128 v[168:171], v147
	ds_read_b128 v[172:175], v147 offset:1024
	ds_read_b128 v[176:179], v147 offset:2048
	ds_read_b128 v[180:183], v147 offset:3072
	s_add_u32 s42, s42, 0x40000
	s_addc_u32 s43, s43, 0
	s_mov_b32 m0, s53
	v_lshl_add_u64 v[222:223], s[42:43], 0, v[134:135]
	ds_read_b128 v[184:187], v144 offset:32768
	ds_read_b128 v[188:191], v144 offset:33792
	ds_read_b128 v[192:195], v144 offset:34816
	ds_read_b128 v[196:199], v144 offset:35840
	ds_read_b128 v[200:203], v144 offset:36864
	ds_read_b128 v[204:207], v144 offset:37888
	ds_read_b128 v[208:211], v144 offset:38912
	ds_read_b128 v[212:215], v144 offset:39936
	global_load_lds_dwordx4 v[222:223], off
	v_lshl_add_u64 v[222:223], s[42:43], 0, v[130:131]
	s_mov_b32 m0, s54
	s_nop 0
	global_load_lds_dwordx4 v[222:223], off
	s_waitcnt vmcnt(8)
	s_waitcnt lgkmcnt(0)
	s_barrier
	s_setprio 1
	s_waitcnt lgkmcnt(0)
	v_mfma_f32_16x16x32_bf16 v[124:127], v[148:151], v[184:187], v[124:127]
	v_mfma_f32_16x16x32_bf16 v[120:123], v[160:163], v[184:187], v[120:123]
	v_mfma_f32_16x16x32_bf16 v[116:119], v[148:151], v[192:195], v[116:119]
	v_mfma_f32_16x16x32_bf16 v[112:115], v[160:163], v[192:195], v[112:115]
	v_mfma_f32_16x16x32_bf16 v[100:103], v[148:151], v[200:203], v[100:103]
	v_mfma_f32_16x16x32_bf16 v[96:99], v[160:163], v[200:203], v[96:99]
	v_mfma_f32_16x16x32_bf16 v[84:87], v[148:151], v[208:211], v[84:87]
	v_mfma_f32_16x16x32_bf16 v[80:83], v[160:163], v[208:211], v[80:83]
	v_mfma_f32_16x16x32_bf16 v[124:127], v[156:159], v[188:191], v[124:127]
	v_mfma_f32_16x16x32_bf16 v[120:123], v[164:167], v[188:191], v[120:123]
	v_mfma_f32_16x16x32_bf16 v[116:119], v[156:159], v[196:199], v[116:119]
	v_mfma_f32_16x16x32_bf16 v[112:115], v[164:167], v[196:199], v[112:115]
	v_mfma_f32_16x16x32_bf16 v[100:103], v[156:159], v[204:207], v[100:103]
	v_mfma_f32_16x16x32_bf16 v[96:99], v[164:167], v[204:207], v[96:99]
	v_mfma_f32_16x16x32_bf16 v[84:87], v[156:159], v[212:215], v[84:87]
	v_mfma_f32_16x16x32_bf16 v[80:83], v[164:167], v[212:215], v[80:83]
	v_mfma_f32_16x16x32_bf16 v[108:111], v[168:171], v[184:187], v[108:111]
	v_mfma_f32_16x16x32_bf16 v[104:107], v[176:179], v[184:187], v[104:107]
	v_mfma_f32_16x16x32_bf16 v[92:95], v[168:171], v[192:195], v[92:95]
	v_mfma_f32_16x16x32_bf16 v[88:91], v[176:179], v[192:195], v[88:91]
	v_mfma_f32_16x16x32_bf16 v[76:79], v[168:171], v[200:203], v[76:79]
	v_mfma_f32_16x16x32_bf16 v[72:75], v[176:179], v[200:203], v[72:75]
	v_mfma_f32_16x16x32_bf16 v[68:71], v[168:171], v[208:211], v[68:71]
	v_mfma_f32_16x16x32_bf16 v[64:67], v[176:179], v[208:211], v[64:67]
	v_mfma_f32_16x16x32_bf16 v[108:111], v[172:175], v[188:191], v[108:111]
	v_mfma_f32_16x16x32_bf16 v[104:107], v[180:183], v[188:191], v[104:107]
	v_mfma_f32_16x16x32_bf16 v[92:95], v[172:175], v[196:199], v[92:95]
	v_mfma_f32_16x16x32_bf16 v[88:91], v[180:183], v[196:199], v[88:91]
	v_mfma_f32_16x16x32_bf16 v[76:79], v[172:175], v[204:207], v[76:79]
	v_mfma_f32_16x16x32_bf16 v[72:75], v[180:183], v[204:207], v[72:75]
	v_mfma_f32_16x16x32_bf16 v[68:71], v[172:175], v[212:215], v[68:71]
	v_mfma_f32_16x16x32_bf16 v[64:67], v[180:183], v[212:215], v[64:67]
	s_setprio 0
	s_barrier
	s_add_i32 s42, s59, s50
	v_lshl_add_u64 v[152:153], v[152:153], 0, s[16:17]
	s_mov_b32 m0, s42
	ds_read_b128 v[184:187], v144 offset:49152
	ds_read_b128 v[188:191], v144 offset:50176
	ds_read_b128 v[192:195], v144 offset:51200
	ds_read_b128 v[196:199], v144 offset:52224
	ds_read_b128 v[200:203], v144 offset:53248
	ds_read_b128 v[204:207], v144 offset:54272
	ds_read_b128 v[208:211], v144 offset:55296
	ds_read_b128 v[212:215], v144 offset:56320
	global_load_lds_dwordx4 v[152:153], off
	s_add_i32 m0, s42, 0x2000
	s_add_u32 s40, s40, 0x40080
	v_lshl_add_u64 v[152:153], v[216:217], 0, s[16:17]
	s_addc_u32 s41, s41, 0
	s_add_i32 s42, s60, s50
	global_load_lds_dwordx4 v[152:153], off
	v_lshl_add_u64 v[152:153], s[40:41], 0, v[132:133]
	s_mov_b32 m0, s42
	s_nop 0
	global_load_lds_dwordx4 v[152:153], off
	v_lshl_add_u64 v[152:153], s[40:41], 0, v[128:129]
	s_add_i32 m0, s42, 0x2000
	s_nop 0
	global_load_lds_dwordx4 v[152:153], off
	v_lshl_add_u64 v[152:153], v[218:219], 0, s[16:17]
	s_mov_b32 m0, s55
	s_nop 0
	global_load_lds_dwordx4 v[152:153], off
	v_lshl_add_u64 v[152:153], v[220:221], 0, s[16:17]
	s_mov_b32 m0, s56
	s_nop 0
	global_load_lds_dwordx4 v[152:153], off
	s_waitcnt vmcnt(8)
	s_waitcnt lgkmcnt(0)
	s_barrier
	s_setprio 1
	s_waitcnt lgkmcnt(0)
	v_mfma_f32_16x16x32_bf16 v[60:63], v[148:151], v[184:187], v[60:63]
	v_mfma_f32_16x16x32_bf16 v[56:59], v[160:163], v[184:187], v[56:59]
	v_mfma_f32_16x16x32_bf16 v[52:55], v[148:151], v[192:195], v[52:55]
	v_mfma_f32_16x16x32_bf16 v[48:51], v[160:163], v[192:195], v[48:51]
	v_mfma_f32_16x16x32_bf16 v[36:39], v[148:151], v[200:203], v[36:39]
	v_mfma_f32_16x16x32_bf16 v[32:35], v[160:163], v[200:203], v[32:35]
	v_mfma_f32_16x16x32_bf16 v[20:23], v[148:151], v[208:211], v[20:23]
	v_mfma_f32_16x16x32_bf16 v[16:19], v[160:163], v[208:211], v[16:19]
	v_mfma_f32_16x16x32_bf16 v[60:63], v[156:159], v[188:191], v[60:63]
	v_mfma_f32_16x16x32_bf16 v[56:59], v[164:167], v[188:191], v[56:59]
	v_mfma_f32_16x16x32_bf16 v[52:55], v[156:159], v[196:199], v[52:55]
	v_mfma_f32_16x16x32_bf16 v[48:51], v[164:167], v[196:199], v[48:51]
	v_mfma_f32_16x16x32_bf16 v[36:39], v[156:159], v[204:207], v[36:39]
	v_mfma_f32_16x16x32_bf16 v[32:35], v[164:167], v[204:207], v[32:35]
	v_mfma_f32_16x16x32_bf16 v[20:23], v[156:159], v[212:215], v[20:23]
	v_mfma_f32_16x16x32_bf16 v[16:19], v[164:167], v[212:215], v[16:19]
	v_mfma_f32_16x16x32_bf16 v[44:47], v[168:171], v[184:187], v[44:47]
	v_mfma_f32_16x16x32_bf16 v[40:43], v[176:179], v[184:187], v[40:43]
	v_mfma_f32_16x16x32_bf16 v[28:31], v[168:171], v[192:195], v[28:31]
	v_mfma_f32_16x16x32_bf16 v[24:27], v[176:179], v[192:195], v[24:27]
	v_mfma_f32_16x16x32_bf16 v[12:15], v[168:171], v[200:203], v[12:15]
	v_mfma_f32_16x16x32_bf16 v[8:11], v[176:179], v[200:203], v[8:11]
	v_mfma_f32_16x16x32_bf16 v[4:7], v[168:171], v[208:211], v[4:7]
	v_mfma_f32_16x16x32_bf16 v[0:3], v[176:179], v[208:211], v[0:3]
	v_mfma_f32_16x16x32_bf16 v[44:47], v[172:175], v[188:191], v[44:47]
	v_mfma_f32_16x16x32_bf16 v[40:43], v[180:183], v[188:191], v[40:43]
	v_mfma_f32_16x16x32_bf16 v[28:31], v[172:175], v[196:199], v[28:31]
	v_mfma_f32_16x16x32_bf16 v[24:27], v[180:183], v[196:199], v[24:27]
	v_mfma_f32_16x16x32_bf16 v[12:15], v[172:175], v[204:207], v[12:15]
	v_mfma_f32_16x16x32_bf16 v[8:11], v[180:183], v[204:207], v[8:11]
	v_mfma_f32_16x16x32_bf16 v[4:7], v[172:175], v[212:215], v[4:7]
	v_mfma_f32_16x16x32_bf16 v[0:3], v[180:183], v[212:215], v[0:3]
	s_setprio 0
	s_barrier
	s_add_i32 s64, s64, 2
	s_add_u32 s38, s38, 0x100
	s_addc_u32 s39, s39, 0
	s_add_u32 s62, s62, 0x100
	s_addc_u32 s63, s63, 0
	s_cmp_gt_u32 s64, 13
	s_cbranch_scc0 .LBB0_842
	s_and_b64 vcc, exec, s[18:19]
	s_cbranch_vccz .LBB0_845
	s_barrier

.LBB0_940:
	ds_read_b128 v[156:159], v147
	ds_read_b128 v[160:163], v147 offset:1024
	ds_read_b128 v[164:167], v147 offset:2048
	ds_read_b128 v[168:171], v147 offset:3072
	ds_read_b128 v[172:175], v148
	ds_read_b128 v[176:179], v148 offset:1024
	ds_read_b128 v[180:183], v148 offset:2048
	ds_read_b128 v[184:187], v148 offset:3072
	s_add_u32 s30, s28, 0xfffc0080
	s_addc_u32 s31, s29, -1
	s_cmp_eq_u32 s61, 12
	s_cselect_b32 s35, s17, s31
	s_cselect_b32 s34, s25, s30
	s_cselect_b32 s31, s19, s60
	s_cselect_b32 s30, s27, s59
	v_lshl_add_u64 v[152:153], s[28:29], 0, v[134:135]
	s_add_i32 m0, s41, 0xc000
	ds_read_b128 v[188:191], v149
	ds_read_b128 v[192:195], v149 offset:1024
	ds_read_b128 v[196:199], v149 offset:2048
	ds_read_b128 v[200:203], v149 offset:3072
	ds_read_b128 v[204:207], v149 offset:4096
	ds_read_b128 v[208:211], v149 offset:5120
	ds_read_b128 v[212:215], v149 offset:6144
	ds_read_b128 v[216:219], v149 offset:7168
	global_load_lds_dwordx4 v[152:153], off
	v_lshl_add_u64 v[152:153], s[28:29], 0, v[136:137]
	s_add_i32 m0, s41, 0xe000
	s_nop 0
	global_load_lds_dwordx4 v[152:153], off
	s_waitcnt vmcnt(8)
	s_waitcnt lgkmcnt(0)
	s_barrier
	s_setprio 1
	s_waitcnt lgkmcnt(0)
	v_mfma_f32_16x16x32_bf16 v[124:127], v[156:159], v[188:191], v[124:127]
	v_mfma_f32_16x16x32_bf16 v[120:123], v[164:167], v[188:191], v[120:123]
	v_mfma_f32_16x16x32_bf16 v[108:111], v[156:159], v[196:199], v[108:111]
	v_mfma_f32_16x16x32_bf16 v[104:107], v[164:167], v[196:199], v[104:107]
	v_mfma_f32_16x16x32_bf16 v[92:95], v[156:159], v[204:207], v[92:95]
	v_mfma_f32_16x16x32_bf16 v[88:91], v[164:167], v[204:207], v[88:91]
	v_mfma_f32_16x16x32_bf16 v[76:79], v[156:159], v[212:215], v[76:79]
	v_mfma_f32_16x16x32_bf16 v[72:75], v[164:167], v[212:215], v[72:75]
	v_mfma_f32_16x16x32_bf16 v[124:127], v[160:163], v[192:195], v[124:127]
	v_mfma_f32_16x16x32_bf16 v[120:123], v[168:171], v[192:195], v[120:123]
	v_mfma_f32_16x16x32_bf16 v[108:111], v[160:163], v[200:203], v[108:111]
	v_mfma_f32_16x16x32_bf16 v[104:107], v[168:171], v[200:203], v[104:107]
	v_mfma_f32_16x16x32_bf16 v[92:95], v[160:163], v[208:211], v[92:95]
	v_mfma_f32_16x16x32_bf16 v[88:91], v[168:171], v[208:211], v[88:91]
	v_mfma_f32_16x16x32_bf16 v[76:79], v[160:163], v[216:219], v[76:79]
	v_mfma_f32_16x16x32_bf16 v[72:75], v[168:171], v[216:219], v[72:75]
	v_mfma_f32_16x16x32_bf16 v[116:119], v[172:175], v[188:191], v[116:119]
	v_mfma_f32_16x16x32_bf16 v[112:115], v[180:183], v[188:191], v[112:115]
	v_mfma_f32_16x16x32_bf16 v[100:103], v[172:175], v[196:199], v[100:103]
	v_mfma_f32_16x16x32_bf16 v[96:99], v[180:183], v[196:199], v[96:99]
	v_mfma_f32_16x16x32_bf16 v[84:87], v[172:175], v[204:207], v[84:87]
	v_mfma_f32_16x16x32_bf16 v[80:83], v[180:183], v[204:207], v[80:83]
	v_mfma_f32_16x16x32_bf16 v[68:71], v[172:175], v[212:215], v[68:71]
	v_mfma_f32_16x16x32_bf16 v[64:67], v[180:183], v[212:215], v[64:67]
	v_mfma_f32_16x16x32_bf16 v[116:119], v[176:179], v[192:195], v[116:119]
	v_mfma_f32_16x16x32_bf16 v[112:115], v[184:187], v[192:195], v[112:115]
	v_mfma_f32_16x16x32_bf16 v[100:103], v[176:179], v[200:203], v[100:103]
	v_mfma_f32_16x16x32_bf16 v[96:99], v[184:187], v[200:203], v[96:99]
	v_mfma_f32_16x16x32_bf16 v[84:87], v[176:179], v[208:211], v[84:87]
	v_mfma_f32_16x16x32_bf16 v[80:83], v[184:187], v[208:211], v[80:83]
	v_mfma_f32_16x16x32_bf16 v[68:71], v[176:179], v[216:219], v[68:71]
	v_mfma_f32_16x16x32_bf16 v[64:67], v[184:187], v[216:219], v[64:67]
	s_setprio 0
	s_barrier
	s_add_i32 s62, s54, s40
	v_lshl_add_u64 v[152:153], s[30:31], 0, v[128:129]
	s_mov_b32 m0, s62
	ds_read_b128 v[188:191], v149 offset:16384
	ds_read_b128 v[192:195], v149 offset:17408
	ds_read_b128 v[196:199], v149 offset:18432
	ds_read_b128 v[200:203], v149 offset:19456
	ds_read_b128 v[204:207], v149 offset:20480
	ds_read_b128 v[208:211], v149 offset:21504
	ds_read_b128 v[212:215], v149 offset:22528
	ds_read_b128 v[216:219], v149 offset:23552
	global_load_lds_dwordx4 v[152:153], off
	s_add_i32 m0, s62, 0x2000
	s_add_u32 s62, s30, 0x40000
	v_lshl_add_u64 v[220:221], s[30:31], 0, v[130:131]
	s_addc_u32 s63, s31, 0
	s_add_i32 s64, s55, s40
	global_load_lds_dwordx4 v[220:221], off
	v_lshl_add_u64 v[222:223], s[62:63], 0, v[128:129]
	s_mov_b32 m0, s64
	v_lshl_add_u64 v[224:225], s[34:35], 0, v[130:131]
	global_load_lds_dwordx4 v[222:223], off
	v_lshl_add_u64 v[222:223], s[62:63], 0, v[130:131]
	s_add_i32 m0, s64, 0x2000
	s_nop 0
	global_load_lds_dwordx4 v[222:223], off
	v_lshl_add_u64 v[222:223], s[34:35], 0, v[128:129]
	s_mov_b32 m0, s41
	s_nop 0
	global_load_lds_dwordx4 v[222:223], off
	s_mov_b32 m0, s42
	s_nop 0
	global_load_lds_dwordx4 v[224:225], off
	s_waitcnt vmcnt(8)
	s_waitcnt lgkmcnt(0)
	s_barrier
	s_setprio 1
	s_waitcnt lgkmcnt(0)
	v_mfma_f32_16x16x32_bf16 v[60:63], v[156:159], v[188:191], v[60:63]
	v_mfma_f32_16x16x32_bf16 v[56:59], v[164:167], v[188:191], v[56:59]
	v_mfma_f32_16x16x32_bf16 v[44:47], v[156:159], v[196:199], v[44:47]
	v_mfma_f32_16x16x32_bf16 v[40:43], v[164:167], v[196:199], v[40:43]
	v_mfma_f32_16x16x32_bf16 v[28:31], v[156:159], v[204:207], v[28:31]
	v_mfma_f32_16x16x32_bf16 v[24:27], v[164:167], v[204:207], v[24:27]
	v_mfma_f32_16x16x32_bf16 v[12:15], v[156:159], v[212:215], v[12:15]
	v_mfma_f32_16x16x32_bf16 v[8:11], v[164:167], v[212:215], v[8:11]
	v_mfma_f32_16x16x32_bf16 v[60:63], v[160:163], v[192:195], v[60:63]
	v_mfma_f32_16x16x32_bf16 v[56:59], v[168:171], v[192:195], v[56:59]
	v_mfma_f32_16x16x32_bf16 v[44:47], v[160:163], v[200:203], v[44:47]
	v_mfma_f32_16x16x32_bf16 v[40:43], v[168:171], v[200:203], v[40:43]
	v_mfma_f32_16x16x32_bf16 v[28:31], v[160:163], v[208:211], v[28:31]
	v_mfma_f32_16x16x32_bf16 v[24:27], v[168:171], v[208:211], v[24:27]
	v_mfma_f32_16x16x32_bf16 v[12:15], v[160:163], v[216:219], v[12:15]
	v_mfma_f32_16x16x32_bf16 v[8:11], v[168:171], v[216:219], v[8:11]
	v_mfma_f32_16x16x32_bf16 v[52:55], v[172:175], v[188:191], v[52:55]
	v_mfma_f32_16x16x32_bf16 v[48:51], v[180:183], v[188:191], v[48:51]
	v_mfma_f32_16x16x32_bf16 v[36:39], v[172:175], v[196:199], v[36:39]
	v_mfma_f32_16x16x32_bf16 v[32:35], v[180:183], v[196:199], v[32:35]
	v_mfma_f32_16x16x32_bf16 v[20:23], v[172:175], v[204:207], v[20:23]
	v_mfma_f32_16x16x32_bf16 v[16:19], v[180:183], v[204:207], v[16:19]
	v_mfma_f32_16x16x32_bf16 v[4:7], v[172:175], v[212:215], v[4:7]
	v_mfma_f32_16x16x32_bf16 v[0:3], v[180:183], v[212:215], v[0:3]
	v_mfma_f32_16x16x32_bf16 v[52:55], v[176:179], v[192:195], v[52:55]
	v_mfma_f32_16x16x32_bf16 v[48:51], v[184:187], v[192:195], v[48:51]
	v_mfma_f32_16x16x32_bf16 v[36:39], v[176:179], v[200:203], v[36:39]
	v_mfma_f32_16x16x32_bf16 v[32:35], v[184:187], v[200:203], v[32:35]
	v_mfma_f32_16x16x32_bf16 v[20:23], v[176:179], v[208:211], v[20:23]
	v_mfma_f32_16x16x32_bf16 v[16:19], v[184:187], v[208:211], v[16:19]
	v_mfma_f32_16x16x32_bf16 v[4:7], v[176:179], v[216:219], v[4:7]
	v_mfma_f32_16x16x32_bf16 v[0:3], v[184:187], v[216:219], v[0:3]
	s_setprio 0
	s_barrier
	ds_read_b128 v[156:159], v150
	ds_read_b128 v[160:163], v150 offset:1024
	ds_read_b128 v[164:167], v150 offset:2048
	ds_read_b128 v[168:171], v150 offset:3072
	ds_read_b128 v[172:175], v151
	ds_read_b128 v[176:179], v151 offset:1024
	ds_read_b128 v[180:183], v151 offset:2048
	ds_read_b128 v[184:187], v151 offset:3072
	s_add_u32 s34, s34, 0x40000
	s_addc_u32 s35, s35, 0
	s_mov_b32 m0, s43
	v_lshl_add_u64 v[226:227], s[34:35], 0, v[128:129]
	ds_read_b128 v[188:191], v149 offset:32768
	ds_read_b128 v[192:195], v149 offset:33792
	ds_read_b128 v[196:199], v149 offset:34816
	ds_read_b128 v[200:203], v149 offset:35840
	ds_read_b128 v[204:207], v149 offset:36864
	ds_read_b128 v[208:211], v149 offset:37888
	ds_read_b128 v[212:215], v149 offset:38912
	ds_read_b128 v[216:219], v149 offset:39936
	global_load_lds_dwordx4 v[226:227], off
	v_lshl_add_u64 v[226:227], s[34:35], 0, v[130:131]
	s_mov_b32 m0, s44
	s_nop 0
	global_load_lds_dwordx4 v[226:227], off
	s_waitcnt vmcnt(8)
	s_waitcnt lgkmcnt(0)
	s_barrier
	s_setprio 1
	s_waitcnt lgkmcnt(0)
	v_mfma_f32_16x16x32_bf16 v[124:127], v[156:159], v[188:191], v[124:127]
	v_mfma_f32_16x16x32_bf16 v[120:123], v[164:167], v[188:191], v[120:123]
	v_mfma_f32_16x16x32_bf16 v[108:111], v[156:159], v[196:199], v[108:111]
	v_mfma_f32_16x16x32_bf16 v[104:107], v[164:167], v[196:199], v[104:107]
	v_mfma_f32_16x16x32_bf16 v[92:95], v[156:159], v[204:207], v[92:95]
	v_mfma_f32_16x16x32_bf16 v[88:91], v[164:167], v[204:207], v[88:91]
	v_mfma_f32_16x16x32_bf16 v[76:79], v[156:159], v[212:215], v[76:79]
	v_mfma_f32_16x16x32_bf16 v[72:75], v[164:167], v[212:215], v[72:75]
	v_mfma_f32_16x16x32_bf16 v[124:127], v[160:163], v[192:195], v[124:127]
	v_mfma_f32_16x16x32_bf16 v[120:123], v[168:171], v[192:195], v[120:123]
	v_mfma_f32_16x16x32_bf16 v[108:111], v[160:163], v[200:203], v[108:111]
	v_mfma_f32_16x16x32_bf16 v[104:107], v[168:171], v[200:203], v[104:107]
	v_mfma_f32_16x16x32_bf16 v[92:95], v[160:163], v[208:211], v[92:95]
	v_mfma_f32_16x16x32_bf16 v[88:91], v[168:171], v[208:211], v[88:91]
	v_mfma_f32_16x16x32_bf16 v[76:79], v[160:163], v[216:219], v[76:79]
	v_mfma_f32_16x16x32_bf16 v[72:75], v[168:171], v[216:219], v[72:75]
	v_mfma_f32_16x16x32_bf16 v[116:119], v[172:175], v[188:191], v[116:119]
	v_mfma_f32_16x16x32_bf16 v[112:115], v[180:183], v[188:191], v[112:115]
	v_mfma_f32_16x16x32_bf16 v[100:103], v[172:175], v[196:199], v[100:103]
	v_mfma_f32_16x16x32_bf16 v[96:99], v[180:183], v[196:199], v[96:99]
	v_mfma_f32_16x16x32_bf16 v[84:87], v[172:175], v[204:207], v[84:87]
	v_mfma_f32_16x16x32_bf16 v[80:83], v[180:183], v[204:207], v[80:83]
	v_mfma_f32_16x16x32_bf16 v[68:71], v[172:175], v[212:215], v[68:71]
	v_mfma_f32_16x16x32_bf16 v[64:67], v[180:183], v[212:215], v[64:67]
	v_mfma_f32_16x16x32_bf16 v[116:119], v[176:179], v[192:195], v[116:119]
	v_mfma_f32_16x16x32_bf16 v[112:115], v[184:187], v[192:195], v[112:115]
	v_mfma_f32_16x16x32_bf16 v[100:103], v[176:179], v[200:203], v[100:103]
	v_mfma_f32_16x16x32_bf16 v[96:99], v[184:187], v[200:203], v[96:99]
	v_mfma_f32_16x16x32_bf16 v[84:87], v[176:179], v[208:211], v[84:87]
	v_mfma_f32_16x16x32_bf16 v[80:83], v[184:187], v[208:211], v[80:83]
	v_mfma_f32_16x16x32_bf16 v[68:71], v[176:179], v[216:219], v[68:71]
	v_mfma_f32_16x16x32_bf16 v[64:67], v[184:187], v[216:219], v[64:67]
	s_setprio 0
	s_barrier
	s_add_i32 s34, s57, s40
	v_lshl_add_u64 v[152:153], v[152:153], 0, s[12:13]
	s_mov_b32 m0, s34
	ds_read_b128 v[188:191], v149 offset:49152
	ds_read_b128 v[192:195], v149 offset:50176
	ds_read_b128 v[196:199], v149 offset:51200
	ds_read_b128 v[200:203], v149 offset:52224
	ds_read_b128 v[204:207], v149 offset:53248
	ds_read_b128 v[208:211], v149 offset:54272
	ds_read_b128 v[212:215], v149 offset:55296
	ds_read_b128 v[216:219], v149 offset:56320
	global_load_lds_dwordx4 v[152:153], off
	s_add_i32 m0, s34, 0x2000
	s_add_u32 s30, s30, 0x40080
	v_lshl_add_u64 v[152:153], v[220:221], 0, s[12:13]
	s_addc_u32 s31, s31, 0
	s_add_i32 s34, s58, s40
	global_load_lds_dwordx4 v[152:153], off
	v_lshl_add_u64 v[152:153], s[30:31], 0, v[128:129]
	s_mov_b32 m0, s34
	s_nop 0
	global_load_lds_dwordx4 v[152:153], off
	v_lshl_add_u64 v[152:153], s[30:31], 0, v[130:131]
	s_add_i32 m0, s34, 0x2000
	s_nop 0
	global_load_lds_dwordx4 v[152:153], off
	v_lshl_add_u64 v[152:153], v[222:223], 0, s[12:13]
	s_mov_b32 m0, s49
	s_nop 0
	global_load_lds_dwordx4 v[152:153], off
	v_lshl_add_u64 v[152:153], v[224:225], 0, s[12:13]
	s_mov_b32 m0, s50
	s_nop 0
	global_load_lds_dwordx4 v[152:153], off
	s_waitcnt vmcnt(8)
	s_waitcnt lgkmcnt(0)
	s_barrier
	s_setprio 1
	s_waitcnt lgkmcnt(0)
	v_mfma_f32_16x16x32_bf16 v[60:63], v[156:159], v[188:191], v[60:63]
	v_mfma_f32_16x16x32_bf16 v[56:59], v[164:167], v[188:191], v[56:59]
	v_mfma_f32_16x16x32_bf16 v[44:47], v[156:159], v[196:199], v[44:47]
	v_mfma_f32_16x16x32_bf16 v[40:43], v[164:167], v[196:199], v[40:43]
	v_mfma_f32_16x16x32_bf16 v[28:31], v[156:159], v[204:207], v[28:31]
	v_mfma_f32_16x16x32_bf16 v[24:27], v[164:167], v[204:207], v[24:27]
	v_mfma_f32_16x16x32_bf16 v[12:15], v[156:159], v[212:215], v[12:15]
	v_mfma_f32_16x16x32_bf16 v[8:11], v[164:167], v[212:215], v[8:11]
	v_mfma_f32_16x16x32_bf16 v[60:63], v[160:163], v[192:195], v[60:63]
	v_mfma_f32_16x16x32_bf16 v[56:59], v[168:171], v[192:195], v[56:59]
	v_mfma_f32_16x16x32_bf16 v[44:47], v[160:163], v[200:203], v[44:47]
	v_mfma_f32_16x16x32_bf16 v[40:43], v[168:171], v[200:203], v[40:43]
	v_mfma_f32_16x16x32_bf16 v[28:31], v[160:163], v[208:211], v[28:31]
	v_mfma_f32_16x16x32_bf16 v[24:27], v[168:171], v[208:211], v[24:27]
	v_mfma_f32_16x16x32_bf16 v[12:15], v[160:163], v[216:219], v[12:15]
	v_mfma_f32_16x16x32_bf16 v[8:11], v[168:171], v[216:219], v[8:11]
	v_mfma_f32_16x16x32_bf16 v[52:55], v[172:175], v[188:191], v[52:55]
	v_mfma_f32_16x16x32_bf16 v[48:51], v[180:183], v[188:191], v[48:51]
	v_mfma_f32_16x16x32_bf16 v[36:39], v[172:175], v[196:199], v[36:39]
	v_mfma_f32_16x16x32_bf16 v[32:35], v[180:183], v[196:199], v[32:35]
	v_mfma_f32_16x16x32_bf16 v[20:23], v[172:175], v[204:207], v[20:23]
	v_mfma_f32_16x16x32_bf16 v[16:19], v[180:183], v[204:207], v[16:19]
	v_mfma_f32_16x16x32_bf16 v[4:7], v[172:175], v[212:215], v[4:7]
	v_mfma_f32_16x16x32_bf16 v[0:3], v[180:183], v[212:215], v[0:3]
	v_mfma_f32_16x16x32_bf16 v[52:55], v[176:179], v[192:195], v[52:55]
	v_mfma_f32_16x16x32_bf16 v[48:51], v[184:187], v[192:195], v[48:51]
	v_mfma_f32_16x16x32_bf16 v[36:39], v[176:179], v[200:203], v[36:39]
	v_mfma_f32_16x16x32_bf16 v[32:35], v[184:187], v[200:203], v[32:35]
	v_mfma_f32_16x16x32_bf16 v[20:23], v[176:179], v[208:211], v[20:23]
	v_mfma_f32_16x16x32_bf16 v[16:19], v[184:187], v[208:211], v[16:19]
	v_mfma_f32_16x16x32_bf16 v[4:7], v[176:179], v[216:219], v[4:7]
	v_mfma_f32_16x16x32_bf16 v[0:3], v[184:187], v[216:219], v[0:3]
	s_setprio 0
	s_barrier
	s_add_i32 s61, s61, 2
	s_add_u32 s28, s28, 0x100
	s_addc_u32 s29, s29, 0
	s_add_u32 s59, s59, 0x100
	s_addc_u32 s60, s60, 0
	s_cmp_gt_u32 s61, 13
	s_cbranch_scc0 .LBB0_940
	s_and_b64 vcc, exec, s[14:15]
	s_cbranch_vccz .LBB0_943
	s_barrier

.LBB0_1335:
	ds_read_b128 v[148:151], v142
	ds_read_b128 v[156:159], v142 offset:1024
	ds_read_b128 v[160:163], v142 offset:2048
	ds_read_b128 v[164:167], v142 offset:3072
	ds_read_b128 v[168:171], v143
	ds_read_b128 v[172:175], v143 offset:1024
	ds_read_b128 v[176:179], v143 offset:2048
	ds_read_b128 v[180:183], v143 offset:3072
	s_add_u32 s34, s30, 0xfffc0080
	s_addc_u32 s35, s31, -1
	s_cmp_eq_u32 s60, 12
	s_cselect_b32 s37, s17, s35
	s_cselect_b32 s36, s21, s34
	s_cselect_b32 s35, s19, s59
	s_cselect_b32 s34, s57, s58
	v_lshl_add_u64 v[152:153], s[30:31], 0, v[136:137]
	s_add_i32 m0, s23, 0xc000
	ds_read_b128 v[184:187], v144
	ds_read_b128 v[188:191], v144 offset:1024
	ds_read_b128 v[192:195], v144 offset:2048
	ds_read_b128 v[196:199], v144 offset:3072
	ds_read_b128 v[200:203], v144 offset:4096
	ds_read_b128 v[204:207], v144 offset:5120
	ds_read_b128 v[208:211], v144 offset:6144
	ds_read_b128 v[212:215], v144 offset:7168
	global_load_lds_dwordx4 v[152:153], off
	v_lshl_add_u64 v[152:153], s[30:31], 0, v[138:139]
	s_add_i32 m0, s23, 0xe000
	s_nop 0
	global_load_lds_dwordx4 v[152:153], off
	s_waitcnt vmcnt(8)
	s_waitcnt lgkmcnt(0)
	s_barrier
	s_setprio 1
	s_waitcnt lgkmcnt(0)
	v_mfma_f32_16x16x32_bf16 v[124:127], v[148:151], v[184:187], v[124:127]
	v_mfma_f32_16x16x32_bf16 v[120:123], v[160:163], v[184:187], v[120:123]
	v_mfma_f32_16x16x32_bf16 v[116:119], v[148:151], v[192:195], v[116:119]
	v_mfma_f32_16x16x32_bf16 v[112:115], v[160:163], v[192:195], v[112:115]
	v_mfma_f32_16x16x32_bf16 v[100:103], v[148:151], v[200:203], v[100:103]
	v_mfma_f32_16x16x32_bf16 v[96:99], v[160:163], v[200:203], v[96:99]
	v_mfma_f32_16x16x32_bf16 v[84:87], v[148:151], v[208:211], v[84:87]
	v_mfma_f32_16x16x32_bf16 v[80:83], v[160:163], v[208:211], v[80:83]
	v_mfma_f32_16x16x32_bf16 v[124:127], v[156:159], v[188:191], v[124:127]
	v_mfma_f32_16x16x32_bf16 v[120:123], v[164:167], v[188:191], v[120:123]
	v_mfma_f32_16x16x32_bf16 v[116:119], v[156:159], v[196:199], v[116:119]
	v_mfma_f32_16x16x32_bf16 v[112:115], v[164:167], v[196:199], v[112:115]
	v_mfma_f32_16x16x32_bf16 v[100:103], v[156:159], v[204:207], v[100:103]
	v_mfma_f32_16x16x32_bf16 v[96:99], v[164:167], v[204:207], v[96:99]
	v_mfma_f32_16x16x32_bf16 v[84:87], v[156:159], v[212:215], v[84:87]
	v_mfma_f32_16x16x32_bf16 v[80:83], v[164:167], v[212:215], v[80:83]
	v_mfma_f32_16x16x32_bf16 v[108:111], v[168:171], v[184:187], v[108:111]
	v_mfma_f32_16x16x32_bf16 v[104:107], v[176:179], v[184:187], v[104:107]
	v_mfma_f32_16x16x32_bf16 v[92:95], v[168:171], v[192:195], v[92:95]
	v_mfma_f32_16x16x32_bf16 v[88:91], v[176:179], v[192:195], v[88:91]
	v_mfma_f32_16x16x32_bf16 v[76:79], v[168:171], v[200:203], v[76:79]
	v_mfma_f32_16x16x32_bf16 v[72:75], v[176:179], v[200:203], v[72:75]
	v_mfma_f32_16x16x32_bf16 v[68:71], v[168:171], v[208:211], v[68:71]
	v_mfma_f32_16x16x32_bf16 v[64:67], v[176:179], v[208:211], v[64:67]
	v_mfma_f32_16x16x32_bf16 v[108:111], v[172:175], v[188:191], v[108:111]
	v_mfma_f32_16x16x32_bf16 v[104:107], v[180:183], v[188:191], v[104:107]
	v_mfma_f32_16x16x32_bf16 v[92:95], v[172:175], v[196:199], v[92:95]
	v_mfma_f32_16x16x32_bf16 v[88:91], v[180:183], v[196:199], v[88:91]
	v_mfma_f32_16x16x32_bf16 v[76:79], v[172:175], v[204:207], v[76:79]
	v_mfma_f32_16x16x32_bf16 v[72:75], v[180:183], v[204:207], v[72:75]
	v_mfma_f32_16x16x32_bf16 v[68:71], v[172:175], v[212:215], v[68:71]
	v_mfma_f32_16x16x32_bf16 v[64:67], v[180:183], v[212:215], v[64:67]
	s_setprio 0
	s_barrier
	s_add_i32 s61, s53, s46
	v_lshl_add_u64 v[152:153], s[34:35], 0, v[132:133]
	s_mov_b32 m0, s61
	ds_read_b128 v[184:187], v144 offset:16384
	ds_read_b128 v[188:191], v144 offset:17408
	ds_read_b128 v[192:195], v144 offset:18432
	ds_read_b128 v[196:199], v144 offset:19456
	ds_read_b128 v[200:203], v144 offset:20480
	ds_read_b128 v[204:207], v144 offset:21504
	ds_read_b128 v[208:211], v144 offset:22528
	ds_read_b128 v[212:215], v144 offset:23552
	global_load_lds_dwordx4 v[152:153], off
	s_add_i32 m0, s61, 0x2000
	s_add_u32 s62, s34, 0x40000
	v_lshl_add_u64 v[216:217], s[34:35], 0, v[128:129]
	s_addc_u32 s63, s35, 0
	s_add_i32 s61, s54, s46
	global_load_lds_dwordx4 v[216:217], off
	v_lshl_add_u64 v[218:219], s[62:63], 0, v[132:133]
	s_mov_b32 m0, s61
	v_lshl_add_u64 v[220:221], s[36:37], 0, v[130:131]
	global_load_lds_dwordx4 v[218:219], off
	v_lshl_add_u64 v[218:219], s[62:63], 0, v[128:129]
	s_add_i32 m0, s61, 0x2000
	s_nop 0
	global_load_lds_dwordx4 v[218:219], off
	v_lshl_add_u64 v[218:219], s[36:37], 0, v[134:135]
	s_mov_b32 m0, s23
	s_nop 0
	global_load_lds_dwordx4 v[218:219], off
	s_mov_b32 m0, s48
	s_nop 0
	global_load_lds_dwordx4 v[220:221], off
	s_waitcnt vmcnt(8)
	s_waitcnt lgkmcnt(0)
	s_barrier
	s_setprio 1
	s_waitcnt lgkmcnt(0)
	v_mfma_f32_16x16x32_bf16 v[60:63], v[148:151], v[184:187], v[60:63]
	v_mfma_f32_16x16x32_bf16 v[56:59], v[160:163], v[184:187], v[56:59]
	v_mfma_f32_16x16x32_bf16 v[52:55], v[148:151], v[192:195], v[52:55]
	v_mfma_f32_16x16x32_bf16 v[48:51], v[160:163], v[192:195], v[48:51]
	v_mfma_f32_16x16x32_bf16 v[36:39], v[148:151], v[200:203], v[36:39]
	v_mfma_f32_16x16x32_bf16 v[32:35], v[160:163], v[200:203], v[32:35]
	v_mfma_f32_16x16x32_bf16 v[20:23], v[148:151], v[208:211], v[20:23]
	v_mfma_f32_16x16x32_bf16 v[16:19], v[160:163], v[208:211], v[16:19]
	v_mfma_f32_16x16x32_bf16 v[60:63], v[156:159], v[188:191], v[60:63]
	v_mfma_f32_16x16x32_bf16 v[56:59], v[164:167], v[188:191], v[56:59]
	v_mfma_f32_16x16x32_bf16 v[52:55], v[156:159], v[196:199], v[52:55]
	v_mfma_f32_16x16x32_bf16 v[48:51], v[164:167], v[196:199], v[48:51]
	v_mfma_f32_16x16x32_bf16 v[36:39], v[156:159], v[204:207], v[36:39]
	v_mfma_f32_16x16x32_bf16 v[32:35], v[164:167], v[204:207], v[32:35]
	v_mfma_f32_16x16x32_bf16 v[20:23], v[156:159], v[212:215], v[20:23]
	v_mfma_f32_16x16x32_bf16 v[16:19], v[164:167], v[212:215], v[16:19]
	v_mfma_f32_16x16x32_bf16 v[44:47], v[168:171], v[184:187], v[44:47]
	v_mfma_f32_16x16x32_bf16 v[40:43], v[176:179], v[184:187], v[40:43]
	v_mfma_f32_16x16x32_bf16 v[28:31], v[168:171], v[192:195], v[28:31]
	v_mfma_f32_16x16x32_bf16 v[24:27], v[176:179], v[192:195], v[24:27]
	v_mfma_f32_16x16x32_bf16 v[12:15], v[168:171], v[200:203], v[12:15]
	v_mfma_f32_16x16x32_bf16 v[8:11], v[176:179], v[200:203], v[8:11]
	v_mfma_f32_16x16x32_bf16 v[4:7], v[168:171], v[208:211], v[4:7]
	v_mfma_f32_16x16x32_bf16 v[0:3], v[176:179], v[208:211], v[0:3]
	v_mfma_f32_16x16x32_bf16 v[44:47], v[172:175], v[188:191], v[44:47]
	v_mfma_f32_16x16x32_bf16 v[40:43], v[180:183], v[188:191], v[40:43]
	v_mfma_f32_16x16x32_bf16 v[28:31], v[172:175], v[196:199], v[28:31]
	v_mfma_f32_16x16x32_bf16 v[24:27], v[180:183], v[196:199], v[24:27]
	v_mfma_f32_16x16x32_bf16 v[12:15], v[172:175], v[204:207], v[12:15]
	v_mfma_f32_16x16x32_bf16 v[8:11], v[180:183], v[204:207], v[8:11]
	v_mfma_f32_16x16x32_bf16 v[4:7], v[172:175], v[212:215], v[4:7]
	v_mfma_f32_16x16x32_bf16 v[0:3], v[180:183], v[212:215], v[0:3]
	s_setprio 0
	s_barrier
	ds_read_b128 v[148:151], v145
	ds_read_b128 v[156:159], v145 offset:1024
	ds_read_b128 v[160:163], v145 offset:2048
	ds_read_b128 v[164:167], v145 offset:3072
	ds_read_b128 v[168:171], v147
	ds_read_b128 v[172:175], v147 offset:1024
	ds_read_b128 v[176:179], v147 offset:2048
	ds_read_b128 v[180:183], v147 offset:3072
	s_add_u32 s36, s36, 0x40000
	s_addc_u32 s37, s37, 0
	s_mov_b32 m0, s49
	v_lshl_add_u64 v[222:223], s[36:37], 0, v[134:135]
	ds_read_b128 v[184:187], v144 offset:32768
	ds_read_b128 v[188:191], v144 offset:33792
	ds_read_b128 v[192:195], v144 offset:34816
	ds_read_b128 v[196:199], v144 offset:35840
	ds_read_b128 v[200:203], v144 offset:36864
	ds_read_b128 v[204:207], v144 offset:37888
	ds_read_b128 v[208:211], v144 offset:38912
	ds_read_b128 v[212:215], v144 offset:39936
	global_load_lds_dwordx4 v[222:223], off
	v_lshl_add_u64 v[222:223], s[36:37], 0, v[130:131]
	s_mov_b32 m0, s50
	s_nop 0
	global_load_lds_dwordx4 v[222:223], off
	s_waitcnt vmcnt(8)
	s_waitcnt lgkmcnt(0)
	s_barrier
	s_setprio 1
	s_waitcnt lgkmcnt(0)
	v_mfma_f32_16x16x32_bf16 v[124:127], v[148:151], v[184:187], v[124:127]
	v_mfma_f32_16x16x32_bf16 v[120:123], v[160:163], v[184:187], v[120:123]
	v_mfma_f32_16x16x32_bf16 v[116:119], v[148:151], v[192:195], v[116:119]
	v_mfma_f32_16x16x32_bf16 v[112:115], v[160:163], v[192:195], v[112:115]
	v_mfma_f32_16x16x32_bf16 v[100:103], v[148:151], v[200:203], v[100:103]
	v_mfma_f32_16x16x32_bf16 v[96:99], v[160:163], v[200:203], v[96:99]
	v_mfma_f32_16x16x32_bf16 v[84:87], v[148:151], v[208:211], v[84:87]
	v_mfma_f32_16x16x32_bf16 v[80:83], v[160:163], v[208:211], v[80:83]
	v_mfma_f32_16x16x32_bf16 v[124:127], v[156:159], v[188:191], v[124:127]
	v_mfma_f32_16x16x32_bf16 v[120:123], v[164:167], v[188:191], v[120:123]
	v_mfma_f32_16x16x32_bf16 v[116:119], v[156:159], v[196:199], v[116:119]
	v_mfma_f32_16x16x32_bf16 v[112:115], v[164:167], v[196:199], v[112:115]
	v_mfma_f32_16x16x32_bf16 v[100:103], v[156:159], v[204:207], v[100:103]
	v_mfma_f32_16x16x32_bf16 v[96:99], v[164:167], v[204:207], v[96:99]
	v_mfma_f32_16x16x32_bf16 v[84:87], v[156:159], v[212:215], v[84:87]
	v_mfma_f32_16x16x32_bf16 v[80:83], v[164:167], v[212:215], v[80:83]
	v_mfma_f32_16x16x32_bf16 v[108:111], v[168:171], v[184:187], v[108:111]
	v_mfma_f32_16x16x32_bf16 v[104:107], v[176:179], v[184:187], v[104:107]
	v_mfma_f32_16x16x32_bf16 v[92:95], v[168:171], v[192:195], v[92:95]
	v_mfma_f32_16x16x32_bf16 v[88:91], v[176:179], v[192:195], v[88:91]
	v_mfma_f32_16x16x32_bf16 v[76:79], v[168:171], v[200:203], v[76:79]
	v_mfma_f32_16x16x32_bf16 v[72:75], v[176:179], v[200:203], v[72:75]
	v_mfma_f32_16x16x32_bf16 v[68:71], v[168:171], v[208:211], v[68:71]
	v_mfma_f32_16x16x32_bf16 v[64:67], v[176:179], v[208:211], v[64:67]
	v_mfma_f32_16x16x32_bf16 v[108:111], v[172:175], v[188:191], v[108:111]
	v_mfma_f32_16x16x32_bf16 v[104:107], v[180:183], v[188:191], v[104:107]
	v_mfma_f32_16x16x32_bf16 v[92:95], v[172:175], v[196:199], v[92:95]
	v_mfma_f32_16x16x32_bf16 v[88:91], v[180:183], v[196:199], v[88:91]
	v_mfma_f32_16x16x32_bf16 v[76:79], v[172:175], v[204:207], v[76:79]
	v_mfma_f32_16x16x32_bf16 v[72:75], v[180:183], v[204:207], v[72:75]
	v_mfma_f32_16x16x32_bf16 v[68:71], v[172:175], v[212:215], v[68:71]
	v_mfma_f32_16x16x32_bf16 v[64:67], v[180:183], v[212:215], v[64:67]
	s_setprio 0
	s_barrier
	s_add_i32 s36, s55, s46
	v_lshl_add_u64 v[152:153], v[152:153], 0, s[10:11]
	s_mov_b32 m0, s36
	ds_read_b128 v[184:187], v144 offset:49152
	ds_read_b128 v[188:191], v144 offset:50176
	ds_read_b128 v[192:195], v144 offset:51200
	ds_read_b128 v[196:199], v144 offset:52224
	ds_read_b128 v[200:203], v144 offset:53248
	ds_read_b128 v[204:207], v144 offset:54272
	ds_read_b128 v[208:211], v144 offset:55296
	ds_read_b128 v[212:215], v144 offset:56320
	global_load_lds_dwordx4 v[152:153], off
	s_add_i32 m0, s36, 0x2000
	s_add_u32 s34, s34, 0x40080
	v_lshl_add_u64 v[152:153], v[216:217], 0, s[10:11]
	s_addc_u32 s35, s35, 0
	s_add_i32 s36, s56, s46
	global_load_lds_dwordx4 v[152:153], off
	v_lshl_add_u64 v[152:153], s[34:35], 0, v[132:133]
	s_mov_b32 m0, s36
	s_nop 0
	global_load_lds_dwordx4 v[152:153], off
	v_lshl_add_u64 v[152:153], s[34:35], 0, v[128:129]
	s_add_i32 m0, s36, 0x2000
	s_nop 0
	global_load_lds_dwordx4 v[152:153], off
	v_lshl_add_u64 v[152:153], v[218:219], 0, s[10:11]
	s_mov_b32 m0, s51
	s_nop 0
	global_load_lds_dwordx4 v[152:153], off
	v_lshl_add_u64 v[152:153], v[220:221], 0, s[10:11]
	s_mov_b32 m0, s52
	s_nop 0
	global_load_lds_dwordx4 v[152:153], off
	s_waitcnt vmcnt(8)
	s_waitcnt lgkmcnt(0)
	s_barrier
	s_setprio 1
	s_waitcnt lgkmcnt(0)
	v_mfma_f32_16x16x32_bf16 v[60:63], v[148:151], v[184:187], v[60:63]
	v_mfma_f32_16x16x32_bf16 v[56:59], v[160:163], v[184:187], v[56:59]
	v_mfma_f32_16x16x32_bf16 v[52:55], v[148:151], v[192:195], v[52:55]
	v_mfma_f32_16x16x32_bf16 v[48:51], v[160:163], v[192:195], v[48:51]
	v_mfma_f32_16x16x32_bf16 v[36:39], v[148:151], v[200:203], v[36:39]
	v_mfma_f32_16x16x32_bf16 v[32:35], v[160:163], v[200:203], v[32:35]
	v_mfma_f32_16x16x32_bf16 v[20:23], v[148:151], v[208:211], v[20:23]
	v_mfma_f32_16x16x32_bf16 v[16:19], v[160:163], v[208:211], v[16:19]
	v_mfma_f32_16x16x32_bf16 v[60:63], v[156:159], v[188:191], v[60:63]
	v_mfma_f32_16x16x32_bf16 v[56:59], v[164:167], v[188:191], v[56:59]
	v_mfma_f32_16x16x32_bf16 v[52:55], v[156:159], v[196:199], v[52:55]
	v_mfma_f32_16x16x32_bf16 v[48:51], v[164:167], v[196:199], v[48:51]
	v_mfma_f32_16x16x32_bf16 v[36:39], v[156:159], v[204:207], v[36:39]
	v_mfma_f32_16x16x32_bf16 v[32:35], v[164:167], v[204:207], v[32:35]
	v_mfma_f32_16x16x32_bf16 v[20:23], v[156:159], v[212:215], v[20:23]
	v_mfma_f32_16x16x32_bf16 v[16:19], v[164:167], v[212:215], v[16:19]
	v_mfma_f32_16x16x32_bf16 v[44:47], v[168:171], v[184:187], v[44:47]
	v_mfma_f32_16x16x32_bf16 v[40:43], v[176:179], v[184:187], v[40:43]
	v_mfma_f32_16x16x32_bf16 v[28:31], v[168:171], v[192:195], v[28:31]
	v_mfma_f32_16x16x32_bf16 v[24:27], v[176:179], v[192:195], v[24:27]
	v_mfma_f32_16x16x32_bf16 v[12:15], v[168:171], v[200:203], v[12:15]
	v_mfma_f32_16x16x32_bf16 v[8:11], v[176:179], v[200:203], v[8:11]
	v_mfma_f32_16x16x32_bf16 v[4:7], v[168:171], v[208:211], v[4:7]
	v_mfma_f32_16x16x32_bf16 v[0:3], v[176:179], v[208:211], v[0:3]
	v_mfma_f32_16x16x32_bf16 v[44:47], v[172:175], v[188:191], v[44:47]
	v_mfma_f32_16x16x32_bf16 v[40:43], v[180:183], v[188:191], v[40:43]
	v_mfma_f32_16x16x32_bf16 v[28:31], v[172:175], v[196:199], v[28:31]
	v_mfma_f32_16x16x32_bf16 v[24:27], v[180:183], v[196:199], v[24:27]
	v_mfma_f32_16x16x32_bf16 v[12:15], v[172:175], v[204:207], v[12:15]
	v_mfma_f32_16x16x32_bf16 v[8:11], v[180:183], v[204:207], v[8:11]
	v_mfma_f32_16x16x32_bf16 v[4:7], v[172:175], v[212:215], v[4:7]
	v_mfma_f32_16x16x32_bf16 v[0:3], v[180:183], v[212:215], v[0:3]
	s_setprio 0
	s_barrier
	s_add_i32 s60, s60, 2
	s_add_u32 s30, s30, 0x100
	s_addc_u32 s31, s31, 0
	s_add_u32 s58, s58, 0x100
	s_addc_u32 s59, s59, 0
	s_cmp_gt_u32 s60, 13
	s_cbranch_scc0 .LBB0_1335
	s_and_b64 vcc, exec, s[12:13]
	s_cbranch_vccz .LBB0_1338
	s_barrier

.LBB0_1433:
	ds_read_b128 v[156:159], v146
	ds_read_b128 v[160:163], v146 offset:1024
	ds_read_b128 v[164:167], v146 offset:2048
	ds_read_b128 v[168:171], v146 offset:3072
	ds_read_b128 v[172:175], v147
	ds_read_b128 v[176:179], v147 offset:1024
	ds_read_b128 v[180:183], v147 offset:2048
	ds_read_b128 v[184:187], v147 offset:3072
	s_add_u32 s26, s24, 0xfffc0080
	s_addc_u32 s27, s25, -1
	s_cmp_eq_u32 s54, 12
	s_cselect_b32 s29, s17, s27
	s_cselect_b32 s28, s50, s26
	s_cselect_b32 s27, s19, s53
	s_cselect_b32 s26, s51, s52
	v_lshl_add_u64 v[152:153], s[24:25], 0, v[136:137]
	s_add_i32 m0, s15, 0xc000
	ds_read_b128 v[188:191], v148
	ds_read_b128 v[192:195], v148 offset:1024
	ds_read_b128 v[196:199], v148 offset:2048
	ds_read_b128 v[200:203], v148 offset:3072
	ds_read_b128 v[204:207], v148 offset:4096
	ds_read_b128 v[208:211], v148 offset:5120
	ds_read_b128 v[212:215], v148 offset:6144
	ds_read_b128 v[216:219], v148 offset:7168
	global_load_lds_dwordx4 v[152:153], off
	v_lshl_add_u64 v[152:153], s[24:25], 0, v[138:139]
	s_add_i32 m0, s15, 0xe000
	s_nop 0
	global_load_lds_dwordx4 v[152:153], off
	s_waitcnt vmcnt(8)
	s_waitcnt lgkmcnt(0)
	s_barrier
	s_setprio 1
	s_waitcnt lgkmcnt(0)
	v_mfma_f32_16x16x32_bf16 v[124:127], v[156:159], v[188:191], v[124:127]
	v_mfma_f32_16x16x32_bf16 v[120:123], v[164:167], v[188:191], v[120:123]
	v_mfma_f32_16x16x32_bf16 v[116:119], v[156:159], v[196:199], v[116:119]
	v_mfma_f32_16x16x32_bf16 v[112:115], v[164:167], v[196:199], v[112:115]
	v_mfma_f32_16x16x32_bf16 v[100:103], v[156:159], v[204:207], v[100:103]
	v_mfma_f32_16x16x32_bf16 v[96:99], v[164:167], v[204:207], v[96:99]
	v_mfma_f32_16x16x32_bf16 v[84:87], v[156:159], v[212:215], v[84:87]
	v_mfma_f32_16x16x32_bf16 v[80:83], v[164:167], v[212:215], v[80:83]
	v_mfma_f32_16x16x32_bf16 v[124:127], v[160:163], v[192:195], v[124:127]
	v_mfma_f32_16x16x32_bf16 v[120:123], v[168:171], v[192:195], v[120:123]
	v_mfma_f32_16x16x32_bf16 v[116:119], v[160:163], v[200:203], v[116:119]
	v_mfma_f32_16x16x32_bf16 v[112:115], v[168:171], v[200:203], v[112:115]
	v_mfma_f32_16x16x32_bf16 v[100:103], v[160:163], v[208:211], v[100:103]
	v_mfma_f32_16x16x32_bf16 v[96:99], v[168:171], v[208:211], v[96:99]
	v_mfma_f32_16x16x32_bf16 v[84:87], v[160:163], v[216:219], v[84:87]
	v_mfma_f32_16x16x32_bf16 v[80:83], v[168:171], v[216:219], v[80:83]
	v_mfma_f32_16x16x32_bf16 v[108:111], v[172:175], v[188:191], v[108:111]
	v_mfma_f32_16x16x32_bf16 v[104:107], v[180:183], v[188:191], v[104:107]
	v_mfma_f32_16x16x32_bf16 v[92:95], v[172:175], v[196:199], v[92:95]
	v_mfma_f32_16x16x32_bf16 v[88:91], v[180:183], v[196:199], v[88:91]
	v_mfma_f32_16x16x32_bf16 v[76:79], v[172:175], v[204:207], v[76:79]
	v_mfma_f32_16x16x32_bf16 v[72:75], v[180:183], v[204:207], v[72:75]
	v_mfma_f32_16x16x32_bf16 v[68:71], v[172:175], v[212:215], v[68:71]
	v_mfma_f32_16x16x32_bf16 v[64:67], v[180:183], v[212:215], v[64:67]
	v_mfma_f32_16x16x32_bf16 v[108:111], v[176:179], v[192:195], v[108:111]
	v_mfma_f32_16x16x32_bf16 v[104:107], v[184:187], v[192:195], v[104:107]
	v_mfma_f32_16x16x32_bf16 v[92:95], v[176:179], v[200:203], v[92:95]
	v_mfma_f32_16x16x32_bf16 v[88:91], v[184:187], v[200:203], v[88:91]
	v_mfma_f32_16x16x32_bf16 v[76:79], v[176:179], v[208:211], v[76:79]
	v_mfma_f32_16x16x32_bf16 v[72:75], v[184:187], v[208:211], v[72:75]
	v_mfma_f32_16x16x32_bf16 v[68:71], v[176:179], v[216:219], v[68:71]
	v_mfma_f32_16x16x32_bf16 v[64:67], v[184:187], v[216:219], v[64:67]
	s_setprio 0
	s_barrier
	s_add_i32 s55, s45, s13
	v_lshl_add_u64 v[152:153], s[26:27], 0, v[128:129]
	s_mov_b32 m0, s55
	ds_read_b128 v[188:191], v148 offset:16384
	ds_read_b128 v[192:195], v148 offset:17408
	ds_read_b128 v[196:199], v148 offset:18432
	ds_read_b128 v[200:203], v148 offset:19456
	ds_read_b128 v[204:207], v148 offset:20480
	ds_read_b128 v[208:211], v148 offset:21504
	ds_read_b128 v[212:215], v148 offset:22528
	ds_read_b128 v[216:219], v148 offset:23552
	global_load_lds_dwordx4 v[152:153], off
	s_add_i32 m0, s55, 0x2000
	s_add_u32 s56, s26, 0x40000
	v_lshl_add_u64 v[220:221], s[26:27], 0, v[130:131]
	s_addc_u32 s57, s27, 0
	s_add_i32 s55, s46, s13
	global_load_lds_dwordx4 v[220:221], off
	v_lshl_add_u64 v[222:223], s[56:57], 0, v[128:129]
	s_mov_b32 m0, s55
	v_lshl_add_u64 v[224:225], s[28:29], 0, v[132:133]
	global_load_lds_dwordx4 v[222:223], off
	v_lshl_add_u64 v[222:223], s[56:57], 0, v[130:131]
	s_add_i32 m0, s55, 0x2000
	s_nop 0
	global_load_lds_dwordx4 v[222:223], off
	v_lshl_add_u64 v[222:223], s[28:29], 0, v[134:135]
	s_mov_b32 m0, s15
	s_nop 0
	global_load_lds_dwordx4 v[222:223], off
	s_mov_b32 m0, s36
	s_nop 0
	global_load_lds_dwordx4 v[224:225], off
	s_waitcnt vmcnt(8)
	s_waitcnt lgkmcnt(0)
	s_barrier
	s_setprio 1
	s_waitcnt lgkmcnt(0)
	v_mfma_f32_16x16x32_bf16 v[60:63], v[156:159], v[188:191], v[60:63]
	v_mfma_f32_16x16x32_bf16 v[56:59], v[164:167], v[188:191], v[56:59]
	v_mfma_f32_16x16x32_bf16 v[52:55], v[156:159], v[196:199], v[52:55]
	v_mfma_f32_16x16x32_bf16 v[48:51], v[164:167], v[196:199], v[48:51]
	v_mfma_f32_16x16x32_bf16 v[36:39], v[156:159], v[204:207], v[36:39]
	v_mfma_f32_16x16x32_bf16 v[32:35], v[164:167], v[204:207], v[32:35]
	v_mfma_f32_16x16x32_bf16 v[20:23], v[156:159], v[212:215], v[20:23]
	v_mfma_f32_16x16x32_bf16 v[16:19], v[164:167], v[212:215], v[16:19]
	v_mfma_f32_16x16x32_bf16 v[60:63], v[160:163], v[192:195], v[60:63]
	v_mfma_f32_16x16x32_bf16 v[56:59], v[168:171], v[192:195], v[56:59]
	v_mfma_f32_16x16x32_bf16 v[52:55], v[160:163], v[200:203], v[52:55]
	v_mfma_f32_16x16x32_bf16 v[48:51], v[168:171], v[200:203], v[48:51]
	v_mfma_f32_16x16x32_bf16 v[36:39], v[160:163], v[208:211], v[36:39]
	v_mfma_f32_16x16x32_bf16 v[32:35], v[168:171], v[208:211], v[32:35]
	v_mfma_f32_16x16x32_bf16 v[20:23], v[160:163], v[216:219], v[20:23]
	v_mfma_f32_16x16x32_bf16 v[16:19], v[168:171], v[216:219], v[16:19]
	v_mfma_f32_16x16x32_bf16 v[44:47], v[172:175], v[188:191], v[44:47]
	v_mfma_f32_16x16x32_bf16 v[40:43], v[180:183], v[188:191], v[40:43]
	v_mfma_f32_16x16x32_bf16 v[28:31], v[172:175], v[196:199], v[28:31]
	v_mfma_f32_16x16x32_bf16 v[24:27], v[180:183], v[196:199], v[24:27]
	v_mfma_f32_16x16x32_bf16 v[12:15], v[172:175], v[204:207], v[12:15]
	v_mfma_f32_16x16x32_bf16 v[8:11], v[180:183], v[204:207], v[8:11]
	v_mfma_f32_16x16x32_bf16 v[4:7], v[172:175], v[212:215], v[4:7]
	v_mfma_f32_16x16x32_bf16 v[0:3], v[180:183], v[212:215], v[0:3]
	v_mfma_f32_16x16x32_bf16 v[44:47], v[176:179], v[192:195], v[44:47]
	v_mfma_f32_16x16x32_bf16 v[40:43], v[184:187], v[192:195], v[40:43]
	v_mfma_f32_16x16x32_bf16 v[28:31], v[176:179], v[200:203], v[28:31]
	v_mfma_f32_16x16x32_bf16 v[24:27], v[184:187], v[200:203], v[24:27]
	v_mfma_f32_16x16x32_bf16 v[12:15], v[176:179], v[208:211], v[12:15]
	v_mfma_f32_16x16x32_bf16 v[8:11], v[184:187], v[208:211], v[8:11]
	v_mfma_f32_16x16x32_bf16 v[4:7], v[176:179], v[216:219], v[4:7]
	v_mfma_f32_16x16x32_bf16 v[0:3], v[184:187], v[216:219], v[0:3]
	s_setprio 0
	s_barrier
	ds_read_b128 v[156:159], v149
	ds_read_b128 v[160:163], v149 offset:1024
	ds_read_b128 v[164:167], v149 offset:2048
	ds_read_b128 v[168:171], v149 offset:3072
	ds_read_b128 v[172:175], v150
	ds_read_b128 v[176:179], v150 offset:1024
	ds_read_b128 v[180:183], v150 offset:2048
	ds_read_b128 v[184:187], v150 offset:3072
	s_add_u32 s28, s28, 0x40000
	s_addc_u32 s29, s29, 0
	s_mov_b32 m0, s37
	v_lshl_add_u64 v[226:227], s[28:29], 0, v[134:135]
	ds_read_b128 v[188:191], v148 offset:32768
	ds_read_b128 v[192:195], v148 offset:33792
	ds_read_b128 v[196:199], v148 offset:34816
	ds_read_b128 v[200:203], v148 offset:35840
	ds_read_b128 v[204:207], v148 offset:36864
	ds_read_b128 v[208:211], v148 offset:37888
	ds_read_b128 v[212:215], v148 offset:38912
	ds_read_b128 v[216:219], v148 offset:39936
	global_load_lds_dwordx4 v[226:227], off
	v_lshl_add_u64 v[226:227], s[28:29], 0, v[132:133]
	s_mov_b32 m0, s38
	s_nop 0
	global_load_lds_dwordx4 v[226:227], off
	s_waitcnt vmcnt(8)
	s_waitcnt lgkmcnt(0)
	s_barrier
	s_setprio 1
	s_waitcnt lgkmcnt(0)
	v_mfma_f32_16x16x32_bf16 v[124:127], v[156:159], v[188:191], v[124:127]
	v_mfma_f32_16x16x32_bf16 v[120:123], v[164:167], v[188:191], v[120:123]
	v_mfma_f32_16x16x32_bf16 v[116:119], v[156:159], v[196:199], v[116:119]
	v_mfma_f32_16x16x32_bf16 v[112:115], v[164:167], v[196:199], v[112:115]
	v_mfma_f32_16x16x32_bf16 v[100:103], v[156:159], v[204:207], v[100:103]
	v_mfma_f32_16x16x32_bf16 v[96:99], v[164:167], v[204:207], v[96:99]
	v_mfma_f32_16x16x32_bf16 v[84:87], v[156:159], v[212:215], v[84:87]
	v_mfma_f32_16x16x32_bf16 v[80:83], v[164:167], v[212:215], v[80:83]
	v_mfma_f32_16x16x32_bf16 v[124:127], v[160:163], v[192:195], v[124:127]
	v_mfma_f32_16x16x32_bf16 v[120:123], v[168:171], v[192:195], v[120:123]
	v_mfma_f32_16x16x32_bf16 v[116:119], v[160:163], v[200:203], v[116:119]
	v_mfma_f32_16x16x32_bf16 v[112:115], v[168:171], v[200:203], v[112:115]
	v_mfma_f32_16x16x32_bf16 v[100:103], v[160:163], v[208:211], v[100:103]
	v_mfma_f32_16x16x32_bf16 v[96:99], v[168:171], v[208:211], v[96:99]
	v_mfma_f32_16x16x32_bf16 v[84:87], v[160:163], v[216:219], v[84:87]
	v_mfma_f32_16x16x32_bf16 v[80:83], v[168:171], v[216:219], v[80:83]
	v_mfma_f32_16x16x32_bf16 v[108:111], v[172:175], v[188:191], v[108:111]
	v_mfma_f32_16x16x32_bf16 v[104:107], v[180:183], v[188:191], v[104:107]
	v_mfma_f32_16x16x32_bf16 v[92:95], v[172:175], v[196:199], v[92:95]
	v_mfma_f32_16x16x32_bf16 v[88:91], v[180:183], v[196:199], v[88:91]
	v_mfma_f32_16x16x32_bf16 v[76:79], v[172:175], v[204:207], v[76:79]
	v_mfma_f32_16x16x32_bf16 v[72:75], v[180:183], v[204:207], v[72:75]
	v_mfma_f32_16x16x32_bf16 v[68:71], v[172:175], v[212:215], v[68:71]
	v_mfma_f32_16x16x32_bf16 v[64:67], v[180:183], v[212:215], v[64:67]
	v_mfma_f32_16x16x32_bf16 v[108:111], v[176:179], v[192:195], v[108:111]
	v_mfma_f32_16x16x32_bf16 v[104:107], v[184:187], v[192:195], v[104:107]
	v_mfma_f32_16x16x32_bf16 v[92:95], v[176:179], v[200:203], v[92:95]
	v_mfma_f32_16x16x32_bf16 v[88:91], v[184:187], v[200:203], v[88:91]
	v_mfma_f32_16x16x32_bf16 v[76:79], v[176:179], v[208:211], v[76:79]
	v_mfma_f32_16x16x32_bf16 v[72:75], v[184:187], v[208:211], v[72:75]
	v_mfma_f32_16x16x32_bf16 v[68:71], v[176:179], v[216:219], v[68:71]
	v_mfma_f32_16x16x32_bf16 v[64:67], v[184:187], v[216:219], v[64:67]
	s_setprio 0
	s_barrier
	s_add_i32 s28, s48, s13
	v_lshl_add_u64 v[152:153], v[152:153], 0, s[8:9]
	s_mov_b32 m0, s28
	ds_read_b128 v[188:191], v148 offset:49152
	ds_read_b128 v[192:195], v148 offset:50176
	ds_read_b128 v[196:199], v148 offset:51200
	ds_read_b128 v[200:203], v148 offset:52224
	ds_read_b128 v[204:207], v148 offset:53248
	ds_read_b128 v[208:211], v148 offset:54272
	ds_read_b128 v[212:215], v148 offset:55296
	ds_read_b128 v[216:219], v148 offset:56320
	global_load_lds_dwordx4 v[152:153], off
	s_add_i32 m0, s28, 0x2000
	s_add_u32 s26, s26, 0x40080
	v_lshl_add_u64 v[152:153], v[220:221], 0, s[8:9]
	s_addc_u32 s27, s27, 0
	s_add_i32 s28, s49, s13
	global_load_lds_dwordx4 v[152:153], off
	v_lshl_add_u64 v[152:153], s[26:27], 0, v[128:129]
	s_mov_b32 m0, s28
	s_nop 0
	global_load_lds_dwordx4 v[152:153], off
	v_lshl_add_u64 v[152:153], s[26:27], 0, v[130:131]
	s_add_i32 m0, s28, 0x2000
	s_nop 0
	global_load_lds_dwordx4 v[152:153], off
	v_lshl_add_u64 v[152:153], v[222:223], 0, s[8:9]
	s_mov_b32 m0, s40
	s_nop 0
	global_load_lds_dwordx4 v[152:153], off
	v_lshl_add_u64 v[152:153], v[224:225], 0, s[8:9]
	s_mov_b32 m0, s41
	s_nop 0
	global_load_lds_dwordx4 v[152:153], off
	s_waitcnt vmcnt(8)
	s_waitcnt lgkmcnt(0)
	s_barrier
	s_setprio 1
	s_waitcnt lgkmcnt(0)
	v_mfma_f32_16x16x32_bf16 v[60:63], v[156:159], v[188:191], v[60:63]
	v_mfma_f32_16x16x32_bf16 v[56:59], v[164:167], v[188:191], v[56:59]
	v_mfma_f32_16x16x32_bf16 v[52:55], v[156:159], v[196:199], v[52:55]
	v_mfma_f32_16x16x32_bf16 v[48:51], v[164:167], v[196:199], v[48:51]
	v_mfma_f32_16x16x32_bf16 v[36:39], v[156:159], v[204:207], v[36:39]
	v_mfma_f32_16x16x32_bf16 v[32:35], v[164:167], v[204:207], v[32:35]
	v_mfma_f32_16x16x32_bf16 v[20:23], v[156:159], v[212:215], v[20:23]
	v_mfma_f32_16x16x32_bf16 v[16:19], v[164:167], v[212:215], v[16:19]
	v_mfma_f32_16x16x32_bf16 v[60:63], v[160:163], v[192:195], v[60:63]
	v_mfma_f32_16x16x32_bf16 v[56:59], v[168:171], v[192:195], v[56:59]
	v_mfma_f32_16x16x32_bf16 v[52:55], v[160:163], v[200:203], v[52:55]
	v_mfma_f32_16x16x32_bf16 v[48:51], v[168:171], v[200:203], v[48:51]
	v_mfma_f32_16x16x32_bf16 v[36:39], v[160:163], v[208:211], v[36:39]
	v_mfma_f32_16x16x32_bf16 v[32:35], v[168:171], v[208:211], v[32:35]
	v_mfma_f32_16x16x32_bf16 v[20:23], v[160:163], v[216:219], v[20:23]
	v_mfma_f32_16x16x32_bf16 v[16:19], v[168:171], v[216:219], v[16:19]
	v_mfma_f32_16x16x32_bf16 v[44:47], v[172:175], v[188:191], v[44:47]
	v_mfma_f32_16x16x32_bf16 v[40:43], v[180:183], v[188:191], v[40:43]
	v_mfma_f32_16x16x32_bf16 v[28:31], v[172:175], v[196:199], v[28:31]
	v_mfma_f32_16x16x32_bf16 v[24:27], v[180:183], v[196:199], v[24:27]
	v_mfma_f32_16x16x32_bf16 v[12:15], v[172:175], v[204:207], v[12:15]
	v_mfma_f32_16x16x32_bf16 v[8:11], v[180:183], v[204:207], v[8:11]
	v_mfma_f32_16x16x32_bf16 v[4:7], v[172:175], v[212:215], v[4:7]
	v_mfma_f32_16x16x32_bf16 v[0:3], v[180:183], v[212:215], v[0:3]
	v_mfma_f32_16x16x32_bf16 v[44:47], v[176:179], v[192:195], v[44:47]
	v_mfma_f32_16x16x32_bf16 v[40:43], v[184:187], v[192:195], v[40:43]
	v_mfma_f32_16x16x32_bf16 v[28:31], v[176:179], v[200:203], v[28:31]
	v_mfma_f32_16x16x32_bf16 v[24:27], v[184:187], v[200:203], v[24:27]
	v_mfma_f32_16x16x32_bf16 v[12:15], v[176:179], v[208:211], v[12:15]
	v_mfma_f32_16x16x32_bf16 v[8:11], v[184:187], v[208:211], v[8:11]
	v_mfma_f32_16x16x32_bf16 v[4:7], v[176:179], v[216:219], v[4:7]
	v_mfma_f32_16x16x32_bf16 v[0:3], v[184:187], v[216:219], v[0:3]
	s_setprio 0
	s_barrier
	s_add_i32 s54, s54, 2
	s_add_u32 s24, s24, 0x100
	s_addc_u32 s25, s25, 0
	s_add_u32 s52, s52, 0x100
	s_addc_u32 s53, s53, 0
	s_cmp_gt_u32 s54, 13
	s_cbranch_scc0 .LBB0_1433
	s_and_b64 vcc, exec, s[10:11]
	s_cbranch_vccz .LBB0_1436
	s_barrier

.LBB0_1747:
	ds_read_b128 v[156:159], v146
	ds_read_b128 v[160:163], v146 offset:1024
	ds_read_b128 v[164:167], v146 offset:2048
	ds_read_b128 v[168:171], v146 offset:3072
	ds_read_b128 v[172:175], v147
	ds_read_b128 v[176:179], v147 offset:1024
	ds_read_b128 v[180:183], v147 offset:2048
	ds_read_b128 v[184:187], v147 offset:3072
	s_add_u32 s18, s16, 0xfffb0080
	s_addc_u32 s19, s17, -1
	s_cmp_eq_u32 s49, 16
	s_cselect_b32 s21, s1, s19
	s_cselect_b32 s20, s0, s18
	s_cselect_b32 s19, s15, s48
	s_cselect_b32 s18, s14, s47
	v_lshl_add_u64 v[152:153], s[16:17], 0, v[136:137]
	s_add_i32 m0, s28, 0xc000
	ds_read_b128 v[188:191], v148
	ds_read_b128 v[192:195], v148 offset:1024
	ds_read_b128 v[196:199], v148 offset:2048
	ds_read_b128 v[200:203], v148 offset:3072
	ds_read_b128 v[204:207], v148 offset:4096
	ds_read_b128 v[208:211], v148 offset:5120
	ds_read_b128 v[212:215], v148 offset:6144
	ds_read_b128 v[216:219], v148 offset:7168
	global_load_lds_dwordx4 v[152:153], off
	v_lshl_add_u64 v[152:153], s[16:17], 0, v[138:139]
	s_add_i32 m0, s28, 0xe000
	s_nop 0
	global_load_lds_dwordx4 v[152:153], off
	s_waitcnt vmcnt(8)
	s_waitcnt lgkmcnt(0)
	s_barrier
	s_setprio 1
	s_waitcnt lgkmcnt(0)
	v_mfma_f32_16x16x32_bf16 v[124:127], v[156:159], v[188:191], v[124:127]
	v_mfma_f32_16x16x32_bf16 v[120:123], v[164:167], v[188:191], v[120:123]
	v_mfma_f32_16x16x32_bf16 v[116:119], v[156:159], v[196:199], v[116:119]
	v_mfma_f32_16x16x32_bf16 v[112:115], v[164:167], v[196:199], v[112:115]
	v_mfma_f32_16x16x32_bf16 v[100:103], v[156:159], v[204:207], v[100:103]
	v_mfma_f32_16x16x32_bf16 v[96:99], v[164:167], v[204:207], v[96:99]
	v_mfma_f32_16x16x32_bf16 v[84:87], v[156:159], v[212:215], v[84:87]
	v_mfma_f32_16x16x32_bf16 v[80:83], v[164:167], v[212:215], v[80:83]
	v_mfma_f32_16x16x32_bf16 v[124:127], v[160:163], v[192:195], v[124:127]
	v_mfma_f32_16x16x32_bf16 v[120:123], v[168:171], v[192:195], v[120:123]
	v_mfma_f32_16x16x32_bf16 v[116:119], v[160:163], v[200:203], v[116:119]
	v_mfma_f32_16x16x32_bf16 v[112:115], v[168:171], v[200:203], v[112:115]
	v_mfma_f32_16x16x32_bf16 v[100:103], v[160:163], v[208:211], v[100:103]
	v_mfma_f32_16x16x32_bf16 v[96:99], v[168:171], v[208:211], v[96:99]
	v_mfma_f32_16x16x32_bf16 v[84:87], v[160:163], v[216:219], v[84:87]
	v_mfma_f32_16x16x32_bf16 v[80:83], v[168:171], v[216:219], v[80:83]
	v_mfma_f32_16x16x32_bf16 v[108:111], v[172:175], v[188:191], v[108:111]
	v_mfma_f32_16x16x32_bf16 v[104:107], v[180:183], v[188:191], v[104:107]
	v_mfma_f32_16x16x32_bf16 v[92:95], v[172:175], v[196:199], v[92:95]
	v_mfma_f32_16x16x32_bf16 v[88:91], v[180:183], v[196:199], v[88:91]
	v_mfma_f32_16x16x32_bf16 v[76:79], v[172:175], v[204:207], v[76:79]
	v_mfma_f32_16x16x32_bf16 v[72:75], v[180:183], v[204:207], v[72:75]
	v_mfma_f32_16x16x32_bf16 v[68:71], v[172:175], v[212:215], v[68:71]
	v_mfma_f32_16x16x32_bf16 v[64:67], v[180:183], v[212:215], v[64:67]
	v_mfma_f32_16x16x32_bf16 v[108:111], v[176:179], v[192:195], v[108:111]
	v_mfma_f32_16x16x32_bf16 v[104:107], v[184:187], v[192:195], v[104:107]
	v_mfma_f32_16x16x32_bf16 v[92:95], v[176:179], v[200:203], v[92:95]
	v_mfma_f32_16x16x32_bf16 v[88:91], v[184:187], v[200:203], v[88:91]
	v_mfma_f32_16x16x32_bf16 v[76:79], v[176:179], v[208:211], v[76:79]
	v_mfma_f32_16x16x32_bf16 v[72:75], v[184:187], v[208:211], v[72:75]
	v_mfma_f32_16x16x32_bf16 v[68:71], v[176:179], v[216:219], v[68:71]
	v_mfma_f32_16x16x32_bf16 v[64:67], v[184:187], v[216:219], v[64:67]
	s_setprio 0
	s_barrier
	s_add_i32 s50, s39, s27
	v_lshl_add_u64 v[152:153], s[18:19], 0, v[128:129]
	s_mov_b32 m0, s50
	ds_read_b128 v[188:191], v148 offset:16384
	ds_read_b128 v[192:195], v148 offset:17408
	ds_read_b128 v[196:199], v148 offset:18432
	ds_read_b128 v[200:203], v148 offset:19456
	ds_read_b128 v[204:207], v148 offset:20480
	ds_read_b128 v[208:211], v148 offset:21504
	ds_read_b128 v[212:215], v148 offset:22528
	ds_read_b128 v[216:219], v148 offset:23552
	global_load_lds_dwordx4 v[152:153], off
	s_add_i32 m0, s50, 0x2000
	s_add_u32 s50, s18, 0x50000
	v_lshl_add_u64 v[220:221], s[18:19], 0, v[130:131]
	s_addc_u32 s51, s19, 0
	s_add_i32 s52, s40, s27
	global_load_lds_dwordx4 v[220:221], off
	v_lshl_add_u64 v[222:223], s[50:51], 0, v[128:129]
	s_mov_b32 m0, s52
	v_lshl_add_u64 v[224:225], s[20:21], 0, v[132:133]
	global_load_lds_dwordx4 v[222:223], off
	v_lshl_add_u64 v[222:223], s[50:51], 0, v[130:131]
	s_add_i32 m0, s52, 0x2000
	s_nop 0
	global_load_lds_dwordx4 v[222:223], off
	v_lshl_add_u64 v[222:223], s[20:21], 0, v[134:135]
	s_mov_b32 m0, s28
	s_nop 0
	global_load_lds_dwordx4 v[222:223], off
	s_mov_b32 m0, s29
	s_nop 0
	global_load_lds_dwordx4 v[224:225], off
	s_waitcnt vmcnt(8)
	s_waitcnt lgkmcnt(0)
	s_barrier
	s_setprio 1
	s_waitcnt lgkmcnt(0)
	v_mfma_f32_16x16x32_bf16 v[60:63], v[156:159], v[188:191], v[60:63]
	v_mfma_f32_16x16x32_bf16 v[56:59], v[164:167], v[188:191], v[56:59]
	v_mfma_f32_16x16x32_bf16 v[52:55], v[156:159], v[196:199], v[52:55]
	v_mfma_f32_16x16x32_bf16 v[48:51], v[164:167], v[196:199], v[48:51]
	v_mfma_f32_16x16x32_bf16 v[36:39], v[156:159], v[204:207], v[36:39]
	v_mfma_f32_16x16x32_bf16 v[32:35], v[164:167], v[204:207], v[32:35]
	v_mfma_f32_16x16x32_bf16 v[20:23], v[156:159], v[212:215], v[20:23]
	v_mfma_f32_16x16x32_bf16 v[16:19], v[164:167], v[212:215], v[16:19]
	v_mfma_f32_16x16x32_bf16 v[60:63], v[160:163], v[192:195], v[60:63]
	v_mfma_f32_16x16x32_bf16 v[56:59], v[168:171], v[192:195], v[56:59]
	v_mfma_f32_16x16x32_bf16 v[52:55], v[160:163], v[200:203], v[52:55]
	v_mfma_f32_16x16x32_bf16 v[48:51], v[168:171], v[200:203], v[48:51]
	v_mfma_f32_16x16x32_bf16 v[36:39], v[160:163], v[208:211], v[36:39]
	v_mfma_f32_16x16x32_bf16 v[32:35], v[168:171], v[208:211], v[32:35]
	v_mfma_f32_16x16x32_bf16 v[20:23], v[160:163], v[216:219], v[20:23]
	v_mfma_f32_16x16x32_bf16 v[16:19], v[168:171], v[216:219], v[16:19]
	v_mfma_f32_16x16x32_bf16 v[44:47], v[172:175], v[188:191], v[44:47]
	v_mfma_f32_16x16x32_bf16 v[40:43], v[180:183], v[188:191], v[40:43]
	v_mfma_f32_16x16x32_bf16 v[28:31], v[172:175], v[196:199], v[28:31]
	v_mfma_f32_16x16x32_bf16 v[24:27], v[180:183], v[196:199], v[24:27]
	v_mfma_f32_16x16x32_bf16 v[12:15], v[172:175], v[204:207], v[12:15]
	v_mfma_f32_16x16x32_bf16 v[8:11], v[180:183], v[204:207], v[8:11]
	v_mfma_f32_16x16x32_bf16 v[4:7], v[172:175], v[212:215], v[4:7]
	v_mfma_f32_16x16x32_bf16 v[0:3], v[180:183], v[212:215], v[0:3]
	v_mfma_f32_16x16x32_bf16 v[44:47], v[176:179], v[192:195], v[44:47]
	v_mfma_f32_16x16x32_bf16 v[40:43], v[184:187], v[192:195], v[40:43]
	v_mfma_f32_16x16x32_bf16 v[28:31], v[176:179], v[200:203], v[28:31]
	v_mfma_f32_16x16x32_bf16 v[24:27], v[184:187], v[200:203], v[24:27]
	v_mfma_f32_16x16x32_bf16 v[12:15], v[176:179], v[208:211], v[12:15]
	v_mfma_f32_16x16x32_bf16 v[8:11], v[184:187], v[208:211], v[8:11]
	v_mfma_f32_16x16x32_bf16 v[4:7], v[176:179], v[216:219], v[4:7]
	v_mfma_f32_16x16x32_bf16 v[0:3], v[184:187], v[216:219], v[0:3]
	s_setprio 0
	s_barrier
	ds_read_b128 v[156:159], v149
	ds_read_b128 v[160:163], v149 offset:1024
	ds_read_b128 v[164:167], v149 offset:2048
	ds_read_b128 v[168:171], v149 offset:3072
	ds_read_b128 v[172:175], v150
	ds_read_b128 v[176:179], v150 offset:1024
	ds_read_b128 v[180:183], v150 offset:2048
	ds_read_b128 v[184:187], v150 offset:3072
	s_add_u32 s20, s20, 0x50000
	s_addc_u32 s21, s21, 0
	s_mov_b32 m0, s30
	v_lshl_add_u64 v[226:227], s[20:21], 0, v[134:135]
	ds_read_b128 v[188:191], v148 offset:32768
	ds_read_b128 v[192:195], v148 offset:33792
	ds_read_b128 v[196:199], v148 offset:34816
	ds_read_b128 v[200:203], v148 offset:35840
	ds_read_b128 v[204:207], v148 offset:36864
	ds_read_b128 v[208:211], v148 offset:37888
	ds_read_b128 v[212:215], v148 offset:38912
	ds_read_b128 v[216:219], v148 offset:39936
	global_load_lds_dwordx4 v[226:227], off
	v_lshl_add_u64 v[226:227], s[20:21], 0, v[132:133]
	s_mov_b32 m0, s31
	s_nop 0
	global_load_lds_dwordx4 v[226:227], off
	s_waitcnt vmcnt(8)
	s_waitcnt lgkmcnt(0)
	s_barrier
	s_setprio 1
	s_waitcnt lgkmcnt(0)
	v_mfma_f32_16x16x32_bf16 v[124:127], v[156:159], v[188:191], v[124:127]
	v_mfma_f32_16x16x32_bf16 v[120:123], v[164:167], v[188:191], v[120:123]
	v_mfma_f32_16x16x32_bf16 v[116:119], v[156:159], v[196:199], v[116:119]
	v_mfma_f32_16x16x32_bf16 v[112:115], v[164:167], v[196:199], v[112:115]
	v_mfma_f32_16x16x32_bf16 v[100:103], v[156:159], v[204:207], v[100:103]
	v_mfma_f32_16x16x32_bf16 v[96:99], v[164:167], v[204:207], v[96:99]
	v_mfma_f32_16x16x32_bf16 v[84:87], v[156:159], v[212:215], v[84:87]
	v_mfma_f32_16x16x32_bf16 v[80:83], v[164:167], v[212:215], v[80:83]
	v_mfma_f32_16x16x32_bf16 v[124:127], v[160:163], v[192:195], v[124:127]
	v_mfma_f32_16x16x32_bf16 v[120:123], v[168:171], v[192:195], v[120:123]
	v_mfma_f32_16x16x32_bf16 v[116:119], v[160:163], v[200:203], v[116:119]
	v_mfma_f32_16x16x32_bf16 v[112:115], v[168:171], v[200:203], v[112:115]
	v_mfma_f32_16x16x32_bf16 v[100:103], v[160:163], v[208:211], v[100:103]
	v_mfma_f32_16x16x32_bf16 v[96:99], v[168:171], v[208:211], v[96:99]
	v_mfma_f32_16x16x32_bf16 v[84:87], v[160:163], v[216:219], v[84:87]
	v_mfma_f32_16x16x32_bf16 v[80:83], v[168:171], v[216:219], v[80:83]
	v_mfma_f32_16x16x32_bf16 v[108:111], v[172:175], v[188:191], v[108:111]
	v_mfma_f32_16x16x32_bf16 v[104:107], v[180:183], v[188:191], v[104:107]
	v_mfma_f32_16x16x32_bf16 v[92:95], v[172:175], v[196:199], v[92:95]
	v_mfma_f32_16x16x32_bf16 v[88:91], v[180:183], v[196:199], v[88:91]
	v_mfma_f32_16x16x32_bf16 v[76:79], v[172:175], v[204:207], v[76:79]
	v_mfma_f32_16x16x32_bf16 v[72:75], v[180:183], v[204:207], v[72:75]
	v_mfma_f32_16x16x32_bf16 v[68:71], v[172:175], v[212:215], v[68:71]
	v_mfma_f32_16x16x32_bf16 v[64:67], v[180:183], v[212:215], v[64:67]
	v_mfma_f32_16x16x32_bf16 v[108:111], v[176:179], v[192:195], v[108:111]
	v_mfma_f32_16x16x32_bf16 v[104:107], v[184:187], v[192:195], v[104:107]
	v_mfma_f32_16x16x32_bf16 v[92:95], v[176:179], v[200:203], v[92:95]
	v_mfma_f32_16x16x32_bf16 v[88:91], v[184:187], v[200:203], v[88:91]
	v_mfma_f32_16x16x32_bf16 v[76:79], v[176:179], v[208:211], v[76:79]
	v_mfma_f32_16x16x32_bf16 v[72:75], v[184:187], v[208:211], v[72:75]
	v_mfma_f32_16x16x32_bf16 v[68:71], v[176:179], v[216:219], v[68:71]
	v_mfma_f32_16x16x32_bf16 v[64:67], v[184:187], v[216:219], v[64:67]
	s_setprio 0
	s_barrier
	s_add_i32 s20, s41, s27
	v_lshl_add_u64 v[152:153], v[152:153], 0, s[10:11]
	s_mov_b32 m0, s20
	ds_read_b128 v[188:191], v148 offset:49152
	ds_read_b128 v[192:195], v148 offset:50176
	ds_read_b128 v[196:199], v148 offset:51200
	ds_read_b128 v[200:203], v148 offset:52224
	ds_read_b128 v[204:207], v148 offset:53248
	ds_read_b128 v[208:211], v148 offset:54272
	ds_read_b128 v[212:215], v148 offset:55296
	ds_read_b128 v[216:219], v148 offset:56320
	global_load_lds_dwordx4 v[152:153], off
	s_add_i32 m0, s20, 0x2000
	s_add_u32 s18, s18, 0x50080
	v_lshl_add_u64 v[152:153], v[220:221], 0, s[10:11]
	s_addc_u32 s19, s19, 0
	s_add_i32 s20, s42, s27
	global_load_lds_dwordx4 v[152:153], off
	v_lshl_add_u64 v[152:153], s[18:19], 0, v[128:129]
	s_mov_b32 m0, s20
	s_nop 0
	global_load_lds_dwordx4 v[152:153], off
	v_lshl_add_u64 v[152:153], s[18:19], 0, v[130:131]
	s_add_i32 m0, s20, 0x2000
	s_nop 0
	global_load_lds_dwordx4 v[152:153], off
	v_lshl_add_u64 v[152:153], v[222:223], 0, s[10:11]
	s_mov_b32 m0, s34
	s_nop 0
	global_load_lds_dwordx4 v[152:153], off
	v_lshl_add_u64 v[152:153], v[224:225], 0, s[10:11]
	s_mov_b32 m0, s35
	s_nop 0
	global_load_lds_dwordx4 v[152:153], off
	s_waitcnt vmcnt(8)
	s_waitcnt lgkmcnt(0)
	s_barrier
	s_setprio 1
	s_waitcnt lgkmcnt(0)
	v_mfma_f32_16x16x32_bf16 v[60:63], v[156:159], v[188:191], v[60:63]
	v_mfma_f32_16x16x32_bf16 v[56:59], v[164:167], v[188:191], v[56:59]
	v_mfma_f32_16x16x32_bf16 v[52:55], v[156:159], v[196:199], v[52:55]
	v_mfma_f32_16x16x32_bf16 v[48:51], v[164:167], v[196:199], v[48:51]
	v_mfma_f32_16x16x32_bf16 v[36:39], v[156:159], v[204:207], v[36:39]
	v_mfma_f32_16x16x32_bf16 v[32:35], v[164:167], v[204:207], v[32:35]
	v_mfma_f32_16x16x32_bf16 v[20:23], v[156:159], v[212:215], v[20:23]
	v_mfma_f32_16x16x32_bf16 v[16:19], v[164:167], v[212:215], v[16:19]
	v_mfma_f32_16x16x32_bf16 v[60:63], v[160:163], v[192:195], v[60:63]
	v_mfma_f32_16x16x32_bf16 v[56:59], v[168:171], v[192:195], v[56:59]
	v_mfma_f32_16x16x32_bf16 v[52:55], v[160:163], v[200:203], v[52:55]
	v_mfma_f32_16x16x32_bf16 v[48:51], v[168:171], v[200:203], v[48:51]
	v_mfma_f32_16x16x32_bf16 v[36:39], v[160:163], v[208:211], v[36:39]
	v_mfma_f32_16x16x32_bf16 v[32:35], v[168:171], v[208:211], v[32:35]
	v_mfma_f32_16x16x32_bf16 v[20:23], v[160:163], v[216:219], v[20:23]
	v_mfma_f32_16x16x32_bf16 v[16:19], v[168:171], v[216:219], v[16:19]
	v_mfma_f32_16x16x32_bf16 v[44:47], v[172:175], v[188:191], v[44:47]
	v_mfma_f32_16x16x32_bf16 v[40:43], v[180:183], v[188:191], v[40:43]
	v_mfma_f32_16x16x32_bf16 v[28:31], v[172:175], v[196:199], v[28:31]
	v_mfma_f32_16x16x32_bf16 v[24:27], v[180:183], v[196:199], v[24:27]
	v_mfma_f32_16x16x32_bf16 v[12:15], v[172:175], v[204:207], v[12:15]
	v_mfma_f32_16x16x32_bf16 v[8:11], v[180:183], v[204:207], v[8:11]
	v_mfma_f32_16x16x32_bf16 v[4:7], v[172:175], v[212:215], v[4:7]
	v_mfma_f32_16x16x32_bf16 v[0:3], v[180:183], v[212:215], v[0:3]
	v_mfma_f32_16x16x32_bf16 v[44:47], v[176:179], v[192:195], v[44:47]
	v_mfma_f32_16x16x32_bf16 v[40:43], v[184:187], v[192:195], v[40:43]
	v_mfma_f32_16x16x32_bf16 v[28:31], v[176:179], v[200:203], v[28:31]
	v_mfma_f32_16x16x32_bf16 v[24:27], v[184:187], v[200:203], v[24:27]
	v_mfma_f32_16x16x32_bf16 v[12:15], v[176:179], v[208:211], v[12:15]
	v_mfma_f32_16x16x32_bf16 v[8:11], v[184:187], v[208:211], v[8:11]
	v_mfma_f32_16x16x32_bf16 v[4:7], v[176:179], v[216:219], v[4:7]
	v_mfma_f32_16x16x32_bf16 v[0:3], v[184:187], v[216:219], v[0:3]
	s_setprio 0
	s_barrier
	s_add_i32 s49, s49, 2
	s_add_u32 s16, s16, 0x100
	s_addc_u32 s17, s17, 0
	s_add_u32 s47, s47, 0x100
	s_addc_u32 s48, s48, 0
	s_cmp_gt_u32 s49, 17
	s_cbranch_scc0 .LBB0_1747
	s_and_b64 vcc, exec, s[12:13]
	s_cbranch_vccz .LBB0_1750
	s_barrier

.LBB0_1831:
	ds_read_b128 v[148:151], v142
	ds_read_b128 v[156:159], v142 offset:1024
	ds_read_b128 v[160:163], v142 offset:2048
	ds_read_b128 v[164:167], v142 offset:3072
	ds_read_b128 v[168:171], v143
	ds_read_b128 v[172:175], v143 offset:1024
	ds_read_b128 v[176:179], v143 offset:2048
	ds_read_b128 v[180:183], v143 offset:3072
	s_add_u32 s24, s22, 0xfffb0080
	s_addc_u32 s25, s23, -1
	s_cmp_eq_u32 s58, 16
	s_cselect_b32 s27, s19, s25
	s_cselect_b32 s26, s18, s24
	s_cselect_b32 s25, s21, s57
	s_cselect_b32 s24, s20, s56
	s_mov_b32 m0, s47
	v_lshl_add_u64 v[152:153], s[22:23], 0, v[136:137]
	ds_read_b128 v[184:187], v144
	ds_read_b128 v[188:191], v144 offset:1024
	ds_read_b128 v[192:195], v144 offset:2048
	ds_read_b128 v[196:199], v144 offset:3072
	ds_read_b128 v[200:203], v144 offset:4096
	ds_read_b128 v[204:207], v144 offset:5120
	ds_read_b128 v[208:211], v144 offset:6144
	ds_read_b128 v[212:215], v144 offset:7168
	global_load_lds_dwordx4 v[152:153], off
	v_lshl_add_u64 v[152:153], s[22:23], 0, v[138:139]
	s_mov_b32 m0, s48
	s_nop 0
	global_load_lds_dwordx4 v[152:153], off
	s_waitcnt vmcnt(8)
	s_waitcnt lgkmcnt(0)
	s_barrier
	s_setprio 1
	s_waitcnt lgkmcnt(0)
	v_mfma_f32_16x16x32_bf16 v[124:127], v[148:151], v[184:187], v[124:127]
	v_mfma_f32_16x16x32_bf16 v[120:123], v[160:163], v[184:187], v[120:123]
	v_mfma_f32_16x16x32_bf16 v[116:119], v[148:151], v[192:195], v[116:119]
	v_mfma_f32_16x16x32_bf16 v[112:115], v[160:163], v[192:195], v[112:115]
	v_mfma_f32_16x16x32_bf16 v[100:103], v[148:151], v[200:203], v[100:103]
	v_mfma_f32_16x16x32_bf16 v[96:99], v[160:163], v[200:203], v[96:99]
	v_mfma_f32_16x16x32_bf16 v[84:87], v[148:151], v[208:211], v[84:87]
	v_mfma_f32_16x16x32_bf16 v[80:83], v[160:163], v[208:211], v[80:83]
	v_mfma_f32_16x16x32_bf16 v[124:127], v[156:159], v[188:191], v[124:127]
	v_mfma_f32_16x16x32_bf16 v[120:123], v[164:167], v[188:191], v[120:123]
	v_mfma_f32_16x16x32_bf16 v[116:119], v[156:159], v[196:199], v[116:119]
	v_mfma_f32_16x16x32_bf16 v[112:115], v[164:167], v[196:199], v[112:115]
	v_mfma_f32_16x16x32_bf16 v[100:103], v[156:159], v[204:207], v[100:103]
	v_mfma_f32_16x16x32_bf16 v[96:99], v[164:167], v[204:207], v[96:99]
	v_mfma_f32_16x16x32_bf16 v[84:87], v[156:159], v[212:215], v[84:87]
	v_mfma_f32_16x16x32_bf16 v[80:83], v[164:167], v[212:215], v[80:83]
	v_mfma_f32_16x16x32_bf16 v[108:111], v[168:171], v[184:187], v[108:111]
	v_mfma_f32_16x16x32_bf16 v[104:107], v[176:179], v[184:187], v[104:107]
	v_mfma_f32_16x16x32_bf16 v[92:95], v[168:171], v[192:195], v[92:95]
	v_mfma_f32_16x16x32_bf16 v[88:91], v[176:179], v[192:195], v[88:91]
	v_mfma_f32_16x16x32_bf16 v[76:79], v[168:171], v[200:203], v[76:79]
	v_mfma_f32_16x16x32_bf16 v[72:75], v[176:179], v[200:203], v[72:75]
	v_mfma_f32_16x16x32_bf16 v[68:71], v[168:171], v[208:211], v[68:71]
	v_mfma_f32_16x16x32_bf16 v[64:67], v[176:179], v[208:211], v[64:67]
	v_mfma_f32_16x16x32_bf16 v[108:111], v[172:175], v[188:191], v[108:111]
	v_mfma_f32_16x16x32_bf16 v[104:107], v[180:183], v[188:191], v[104:107]
	v_mfma_f32_16x16x32_bf16 v[92:95], v[172:175], v[196:199], v[92:95]
	v_mfma_f32_16x16x32_bf16 v[88:91], v[180:183], v[196:199], v[88:91]
	v_mfma_f32_16x16x32_bf16 v[76:79], v[172:175], v[204:207], v[76:79]
	v_mfma_f32_16x16x32_bf16 v[72:75], v[180:183], v[204:207], v[72:75]
	v_mfma_f32_16x16x32_bf16 v[68:71], v[172:175], v[212:215], v[68:71]
	v_mfma_f32_16x16x32_bf16 v[64:67], v[180:183], v[212:215], v[64:67]
	s_setprio 0
	s_barrier
	s_mov_b32 m0, s49
	v_lshl_add_u64 v[152:153], s[24:25], 0, v[132:133]
	ds_read_b128 v[184:187], v144 offset:16384
	ds_read_b128 v[188:191], v144 offset:17408
	ds_read_b128 v[192:195], v144 offset:18432
	ds_read_b128 v[196:199], v144 offset:19456
	ds_read_b128 v[200:203], v144 offset:20480
	ds_read_b128 v[204:207], v144 offset:21504
	ds_read_b128 v[208:211], v144 offset:22528
	ds_read_b128 v[212:215], v144 offset:23552
	global_load_lds_dwordx4 v[152:153], off
	s_add_i32 m0, s49, 0x2000
	s_add_u32 s60, s24, 0x50000
	v_lshl_add_u64 v[216:217], s[24:25], 0, v[128:129]
	s_addc_u32 s61, s25, 0
	s_add_i32 s59, s46, s38
	global_load_lds_dwordx4 v[216:217], off
	v_lshl_add_u64 v[218:219], s[60:61], 0, v[132:133]
	s_mov_b32 m0, s59
	v_lshl_add_u64 v[220:221], s[26:27], 0, v[130:131]
	global_load_lds_dwordx4 v[218:219], off
	v_lshl_add_u64 v[218:219], s[60:61], 0, v[128:129]
	s_add_i32 m0, s59, 0x2000
	s_nop 0
	global_load_lds_dwordx4 v[218:219], off
	v_lshl_add_u64 v[218:219], s[26:27], 0, v[134:135]
	s_mov_b32 m0, s40
	s_nop 0
	global_load_lds_dwordx4 v[218:219], off
	s_mov_b32 m0, s41
	s_nop 0
	global_load_lds_dwordx4 v[220:221], off
	s_waitcnt vmcnt(8)
	s_waitcnt lgkmcnt(0)
	s_barrier
	s_setprio 1
	s_waitcnt lgkmcnt(0)
	v_mfma_f32_16x16x32_bf16 v[60:63], v[148:151], v[184:187], v[60:63]
	v_mfma_f32_16x16x32_bf16 v[56:59], v[160:163], v[184:187], v[56:59]
	v_mfma_f32_16x16x32_bf16 v[52:55], v[148:151], v[192:195], v[52:55]
	v_mfma_f32_16x16x32_bf16 v[48:51], v[160:163], v[192:195], v[48:51]
	v_mfma_f32_16x16x32_bf16 v[36:39], v[148:151], v[200:203], v[36:39]
	v_mfma_f32_16x16x32_bf16 v[32:35], v[160:163], v[200:203], v[32:35]
	v_mfma_f32_16x16x32_bf16 v[20:23], v[148:151], v[208:211], v[20:23]
	v_mfma_f32_16x16x32_bf16 v[16:19], v[160:163], v[208:211], v[16:19]
	v_mfma_f32_16x16x32_bf16 v[60:63], v[156:159], v[188:191], v[60:63]
	v_mfma_f32_16x16x32_bf16 v[56:59], v[164:167], v[188:191], v[56:59]
	v_mfma_f32_16x16x32_bf16 v[52:55], v[156:159], v[196:199], v[52:55]
	v_mfma_f32_16x16x32_bf16 v[48:51], v[164:167], v[196:199], v[48:51]
	v_mfma_f32_16x16x32_bf16 v[36:39], v[156:159], v[204:207], v[36:39]
	v_mfma_f32_16x16x32_bf16 v[32:35], v[164:167], v[204:207], v[32:35]
	v_mfma_f32_16x16x32_bf16 v[20:23], v[156:159], v[212:215], v[20:23]
	v_mfma_f32_16x16x32_bf16 v[16:19], v[164:167], v[212:215], v[16:19]
	v_mfma_f32_16x16x32_bf16 v[44:47], v[168:171], v[184:187], v[44:47]
	v_mfma_f32_16x16x32_bf16 v[40:43], v[176:179], v[184:187], v[40:43]
	v_mfma_f32_16x16x32_bf16 v[28:31], v[168:171], v[192:195], v[28:31]
	v_mfma_f32_16x16x32_bf16 v[24:27], v[176:179], v[192:195], v[24:27]
	v_mfma_f32_16x16x32_bf16 v[12:15], v[168:171], v[200:203], v[12:15]
	v_mfma_f32_16x16x32_bf16 v[8:11], v[176:179], v[200:203], v[8:11]
	v_mfma_f32_16x16x32_bf16 v[4:7], v[168:171], v[208:211], v[4:7]
	v_mfma_f32_16x16x32_bf16 v[0:3], v[176:179], v[208:211], v[0:3]
	v_mfma_f32_16x16x32_bf16 v[44:47], v[172:175], v[188:191], v[44:47]
	v_mfma_f32_16x16x32_bf16 v[40:43], v[180:183], v[188:191], v[40:43]
	v_mfma_f32_16x16x32_bf16 v[28:31], v[172:175], v[196:199], v[28:31]
	v_mfma_f32_16x16x32_bf16 v[24:27], v[180:183], v[196:199], v[24:27]
	v_mfma_f32_16x16x32_bf16 v[12:15], v[172:175], v[204:207], v[12:15]
	v_mfma_f32_16x16x32_bf16 v[8:11], v[180:183], v[204:207], v[8:11]
	v_mfma_f32_16x16x32_bf16 v[4:7], v[172:175], v[212:215], v[4:7]
	v_mfma_f32_16x16x32_bf16 v[0:3], v[180:183], v[212:215], v[0:3]
	s_setprio 0
	s_barrier
	ds_read_b128 v[148:151], v145
	ds_read_b128 v[156:159], v145 offset:1024
	ds_read_b128 v[160:163], v145 offset:2048
	ds_read_b128 v[164:167], v145 offset:3072
	ds_read_b128 v[168:171], v147
	ds_read_b128 v[172:175], v147 offset:1024
	ds_read_b128 v[176:179], v147 offset:2048
	ds_read_b128 v[180:183], v147 offset:3072
	s_add_u32 s26, s26, 0x50000
	s_addc_u32 s27, s27, 0
	s_mov_b32 m0, s42
	v_lshl_add_u64 v[222:223], s[26:27], 0, v[134:135]
	ds_read_b128 v[184:187], v144 offset:32768
	ds_read_b128 v[188:191], v144 offset:33792
	ds_read_b128 v[192:195], v144 offset:34816
	ds_read_b128 v[196:199], v144 offset:35840
	ds_read_b128 v[200:203], v144 offset:36864
	ds_read_b128 v[204:207], v144 offset:37888
	ds_read_b128 v[208:211], v144 offset:38912
	ds_read_b128 v[212:215], v144 offset:39936
	global_load_lds_dwordx4 v[222:223], off
	v_lshl_add_u64 v[222:223], s[26:27], 0, v[130:131]
	s_mov_b32 m0, s43
	s_nop 0
	global_load_lds_dwordx4 v[222:223], off
	s_waitcnt vmcnt(8)
	s_waitcnt lgkmcnt(0)
	s_barrier
	s_setprio 1
	s_waitcnt lgkmcnt(0)
	v_mfma_f32_16x16x32_bf16 v[124:127], v[148:151], v[184:187], v[124:127]
	v_mfma_f32_16x16x32_bf16 v[120:123], v[160:163], v[184:187], v[120:123]
	v_mfma_f32_16x16x32_bf16 v[116:119], v[148:151], v[192:195], v[116:119]
	v_mfma_f32_16x16x32_bf16 v[112:115], v[160:163], v[192:195], v[112:115]
	v_mfma_f32_16x16x32_bf16 v[100:103], v[148:151], v[200:203], v[100:103]
	v_mfma_f32_16x16x32_bf16 v[96:99], v[160:163], v[200:203], v[96:99]
	v_mfma_f32_16x16x32_bf16 v[84:87], v[148:151], v[208:211], v[84:87]
	v_mfma_f32_16x16x32_bf16 v[80:83], v[160:163], v[208:211], v[80:83]
	v_mfma_f32_16x16x32_bf16 v[124:127], v[156:159], v[188:191], v[124:127]
	v_mfma_f32_16x16x32_bf16 v[120:123], v[164:167], v[188:191], v[120:123]
	v_mfma_f32_16x16x32_bf16 v[116:119], v[156:159], v[196:199], v[116:119]
	v_mfma_f32_16x16x32_bf16 v[112:115], v[164:167], v[196:199], v[112:115]
	v_mfma_f32_16x16x32_bf16 v[100:103], v[156:159], v[204:207], v[100:103]
	v_mfma_f32_16x16x32_bf16 v[96:99], v[164:167], v[204:207], v[96:99]
	v_mfma_f32_16x16x32_bf16 v[84:87], v[156:159], v[212:215], v[84:87]
	v_mfma_f32_16x16x32_bf16 v[80:83], v[164:167], v[212:215], v[80:83]
	v_mfma_f32_16x16x32_bf16 v[108:111], v[168:171], v[184:187], v[108:111]
	v_mfma_f32_16x16x32_bf16 v[104:107], v[176:179], v[184:187], v[104:107]
	v_mfma_f32_16x16x32_bf16 v[92:95], v[168:171], v[192:195], v[92:95]
	v_mfma_f32_16x16x32_bf16 v[88:91], v[176:179], v[192:195], v[88:91]
	v_mfma_f32_16x16x32_bf16 v[76:79], v[168:171], v[200:203], v[76:79]
	v_mfma_f32_16x16x32_bf16 v[72:75], v[176:179], v[200:203], v[72:75]
	v_mfma_f32_16x16x32_bf16 v[68:71], v[168:171], v[208:211], v[68:71]
	v_mfma_f32_16x16x32_bf16 v[64:67], v[176:179], v[208:211], v[64:67]
	v_mfma_f32_16x16x32_bf16 v[108:111], v[172:175], v[188:191], v[108:111]
	v_mfma_f32_16x16x32_bf16 v[104:107], v[180:183], v[188:191], v[104:107]
	v_mfma_f32_16x16x32_bf16 v[92:95], v[172:175], v[196:199], v[92:95]
	v_mfma_f32_16x16x32_bf16 v[88:91], v[180:183], v[196:199], v[88:91]
	v_mfma_f32_16x16x32_bf16 v[76:79], v[172:175], v[204:207], v[76:79]
	v_mfma_f32_16x16x32_bf16 v[72:75], v[180:183], v[204:207], v[72:75]
	v_mfma_f32_16x16x32_bf16 v[68:71], v[172:175], v[212:215], v[68:71]
	v_mfma_f32_16x16x32_bf16 v[64:67], v[180:183], v[212:215], v[64:67]
	s_setprio 0
	s_barrier
	s_add_i32 s26, s50, s38
	v_lshl_add_u64 v[152:153], v[152:153], 0, s[12:13]
	s_mov_b32 m0, s26
	ds_read_b128 v[184:187], v144 offset:49152
	ds_read_b128 v[188:191], v144 offset:50176
	ds_read_b128 v[192:195], v144 offset:51200
	ds_read_b128 v[196:199], v144 offset:52224
	ds_read_b128 v[200:203], v144 offset:53248
	ds_read_b128 v[204:207], v144 offset:54272
	ds_read_b128 v[208:211], v144 offset:55296
	ds_read_b128 v[212:215], v144 offset:56320
	global_load_lds_dwordx4 v[152:153], off
	s_add_i32 m0, s26, 0x2000
	s_add_u32 s24, s24, 0x50080
	v_lshl_add_u64 v[152:153], v[216:217], 0, s[12:13]
	s_addc_u32 s25, s25, 0
	s_add_i32 s26, s51, s38
	global_load_lds_dwordx4 v[152:153], off
	v_lshl_add_u64 v[152:153], s[24:25], 0, v[132:133]
	s_mov_b32 m0, s26
	s_nop 0
	global_load_lds_dwordx4 v[152:153], off
	v_lshl_add_u64 v[152:153], s[24:25], 0, v[128:129]
	s_add_i32 m0, s26, 0x2000
	s_nop 0
	global_load_lds_dwordx4 v[152:153], off
	v_lshl_add_u64 v[152:153], v[218:219], 0, s[12:13]
	s_mov_b32 m0, s44
	s_nop 0
	global_load_lds_dwordx4 v[152:153], off
	v_lshl_add_u64 v[152:153], v[220:221], 0, s[12:13]
	s_mov_b32 m0, s45
	s_nop 0
	global_load_lds_dwordx4 v[152:153], off
	s_waitcnt vmcnt(8)
	s_waitcnt lgkmcnt(0)
	s_barrier
	s_setprio 1
	s_waitcnt lgkmcnt(0)
	v_mfma_f32_16x16x32_bf16 v[60:63], v[148:151], v[184:187], v[60:63]
	v_mfma_f32_16x16x32_bf16 v[56:59], v[160:163], v[184:187], v[56:59]
	v_mfma_f32_16x16x32_bf16 v[52:55], v[148:151], v[192:195], v[52:55]
	v_mfma_f32_16x16x32_bf16 v[48:51], v[160:163], v[192:195], v[48:51]
	v_mfma_f32_16x16x32_bf16 v[36:39], v[148:151], v[200:203], v[36:39]
	v_mfma_f32_16x16x32_bf16 v[32:35], v[160:163], v[200:203], v[32:35]
	v_mfma_f32_16x16x32_bf16 v[20:23], v[148:151], v[208:211], v[20:23]
	v_mfma_f32_16x16x32_bf16 v[16:19], v[160:163], v[208:211], v[16:19]
	v_mfma_f32_16x16x32_bf16 v[60:63], v[156:159], v[188:191], v[60:63]
	v_mfma_f32_16x16x32_bf16 v[56:59], v[164:167], v[188:191], v[56:59]
	v_mfma_f32_16x16x32_bf16 v[52:55], v[156:159], v[196:199], v[52:55]
	v_mfma_f32_16x16x32_bf16 v[48:51], v[164:167], v[196:199], v[48:51]
	v_mfma_f32_16x16x32_bf16 v[36:39], v[156:159], v[204:207], v[36:39]
	v_mfma_f32_16x16x32_bf16 v[32:35], v[164:167], v[204:207], v[32:35]
	v_mfma_f32_16x16x32_bf16 v[20:23], v[156:159], v[212:215], v[20:23]
	v_mfma_f32_16x16x32_bf16 v[16:19], v[164:167], v[212:215], v[16:19]
	v_mfma_f32_16x16x32_bf16 v[44:47], v[168:171], v[184:187], v[44:47]
	v_mfma_f32_16x16x32_bf16 v[40:43], v[176:179], v[184:187], v[40:43]
	v_mfma_f32_16x16x32_bf16 v[28:31], v[168:171], v[192:195], v[28:31]
	v_mfma_f32_16x16x32_bf16 v[24:27], v[176:179], v[192:195], v[24:27]
	v_mfma_f32_16x16x32_bf16 v[12:15], v[168:171], v[200:203], v[12:15]
	v_mfma_f32_16x16x32_bf16 v[8:11], v[176:179], v[200:203], v[8:11]
	v_mfma_f32_16x16x32_bf16 v[4:7], v[168:171], v[208:211], v[4:7]
	v_mfma_f32_16x16x32_bf16 v[0:3], v[176:179], v[208:211], v[0:3]
	v_mfma_f32_16x16x32_bf16 v[44:47], v[172:175], v[188:191], v[44:47]
	v_mfma_f32_16x16x32_bf16 v[40:43], v[180:183], v[188:191], v[40:43]
	v_mfma_f32_16x16x32_bf16 v[28:31], v[172:175], v[196:199], v[28:31]
	v_mfma_f32_16x16x32_bf16 v[24:27], v[180:183], v[196:199], v[24:27]
	v_mfma_f32_16x16x32_bf16 v[12:15], v[172:175], v[204:207], v[12:15]
	v_mfma_f32_16x16x32_bf16 v[8:11], v[180:183], v[204:207], v[8:11]
	v_mfma_f32_16x16x32_bf16 v[4:7], v[172:175], v[212:215], v[4:7]
	v_mfma_f32_16x16x32_bf16 v[0:3], v[180:183], v[212:215], v[0:3]
	s_setprio 0
	s_barrier
	s_add_i32 s58, s58, 2
	s_add_u32 s22, s22, 0x100
	s_addc_u32 s23, s23, 0
	s_add_u32 s56, s56, 0x100
	s_addc_u32 s57, s57, 0
	s_cmp_gt_u32 s58, 17
	s_cbranch_scc0 .LBB0_1831
	s_and_b64 vcc, exec, s[14:15]
	s_cbranch_vccz .LBB0_1834
	s_barrier
